# v24 + EpiRes (P3/P5/P8/P10) second-half residual loads hoisted next to first-half loads (one load latency per tile instead of two)
# baseline (speedup 1.0000x reference)
.LBB0_404:
	v_lshl_or_b32 v168, s10, 8, v188
	v_lshl_add_u32 v172, s40, 8, v186
	v_ashrrev_i32_e32 v169, 31, v168
	v_lshlrev_b64 v[204:205], 1, v[168:169]
	v_ashrrev_i32_e32 v173, 31, v172
	v_lshl_add_u64 v[170:171], s[16:17], 0, v[204:205]
	v_lshlrev_b64 v[206:207], 11, v[172:173]
	v_lshl_add_u64 v[128:129], v[170:171], 0, v[206:207]
	global_load_dwordx4 v[194:197], v[128:129], off
	global_load_dwordx4 v[198:201], v[128:129], off offset:256
	v_or_b32_e32 v182, 16, v172
	v_or_b32_e32 v178, 32, v172
	v_or_b32_e32 v174, 48, v172
	v_ashrrev_i32_e32 v183, 31, v182
	v_ashrrev_i32_e32 v179, 31, v178
	v_ashrrev_i32_e32 v175, 31, v174
	v_lshlrev_b64 v[184:185], 11, v[182:183]
	v_lshlrev_b64 v[180:181], 11, v[178:179]
	v_lshlrev_b64 v[176:177], 11, v[174:175]
	v_lshl_add_u64 v[128:129], v[170:171], 0, v[184:185]
	v_lshl_add_u64 v[130:131], v[170:171], 0, v[180:181]
	v_lshl_add_u64 v[208:209], v[170:171], 0, v[176:177]
	global_load_dwordx4 v[148:151], v[128:129], off
	global_load_dwordx4 v[144:147], v[128:129], off offset:256
	global_load_dwordx4 v[140:143], v[130:131], off
	global_load_dwordx4 v[136:139], v[130:131], off offset:256
	global_load_dwordx4 v[132:135], v[208:209], off
	s_nop 0
	global_load_dwordx4 v[128:131], v[208:209], off offset:256
	v_add_u32_e32 v248, 0x80, v172
	v_ashrrev_i32_e32 v249, 31, v248
	v_lshlrev_b64 v[248:249], 11, v[248:249]
	v_lshl_add_u64 v[248:249], v[170:171], 0, v[248:249]
	global_load_dwordx4 v[216:219], v[248:249], off
	global_load_dwordx4 v[220:223], v[248:249], off offset:256
	v_add_u32_e32 v250, 0x90, v172
	v_ashrrev_i32_e32 v251, 31, v250
	v_lshlrev_b64 v[250:251], 11, v[250:251]
	v_lshl_add_u64 v[250:251], v[170:171], 0, v[250:251]
	global_load_dwordx4 v[224:227], v[250:251], off
	global_load_dwordx4 v[228:231], v[250:251], off offset:256
	v_add_u32_e32 v252, 0xa0, v172
	v_ashrrev_i32_e32 v253, 31, v252
	v_lshlrev_b64 v[252:253], 11, v[252:253]
	v_lshl_add_u64 v[252:253], v[170:171], 0, v[252:253]
	global_load_dwordx4 v[232:235], v[252:253], off
	global_load_dwordx4 v[236:239], v[252:253], off offset:256
	v_add_u32_e32 v248, 0xb0, v172
	v_ashrrev_i32_e32 v249, 31, v248
	v_lshlrev_b64 v[248:249], 11, v[248:249]
	v_lshl_add_u64 v[248:249], v[170:171], 0, v[248:249]
	global_load_dwordx4 v[240:243], v[248:249], off
	global_load_dwordx4 v[244:247], v[248:249], off offset:256
	v_and_b32_e32 v208, 64, v192
	v_xor_b32_e32 v193, 16, v192
	v_add_u32_e32 v208, 64, v208
	v_xor_b32_e32 v209, 32, v192
	v_cmp_lt_i32_e32 vcc, v193, v208
	v_lshl_add_u64 v[206:207], s[16:17], 0, v[206:207]
	v_lshl_add_u64 v[204:205], v[206:207], 0, v[204:205]
	v_cndmask_b32_e32 v193, v192, v193, vcc
	v_cmp_lt_i32_e32 vcc, v209, v208
	v_lshlrev_b32_e32 v193, 2, v193
	s_lshl_b32 s40, s10, 2
	v_cndmask_b32_e32 v214, v192, v209, vcc
	s_ashr_i32 s41, s40, 31
	s_waitcnt vmcnt(8)
	v_lshlrev_b32_e32 v206, 16, v194
	v_and_b32_e32 v207, 0xffff0000, v194
	v_lshlrev_b32_e32 v194, 16, v195
	v_and_b32_e32 v195, 0xffff0000, v195
	v_lshlrev_b32_e32 v208, 16, v196
	v_and_b32_e32 v209, 0xffff0000, v196
	v_lshlrev_b32_e32 v196, 16, v197
	v_and_b32_e32 v197, 0xffff0000, v197
	v_lshlrev_b32_e32 v210, 16, v198
	v_and_b32_e32 v211, 0xffff0000, v198
	v_lshlrev_b32_e32 v198, 16, v199
	v_and_b32_e32 v199, 0xffff0000, v199
	v_lshlrev_b32_e32 v212, 16, v200
	v_and_b32_e32 v213, 0xffff0000, v200
	v_lshlrev_b32_e32 v200, 16, v201
	v_and_b32_e32 v201, 0xffff0000, v201
	v_pk_add_f32 v[126:127], v[126:127], v[194:195]
	v_pk_add_f32 v[124:125], v[124:125], v[206:207]
	v_pk_add_f32 v[122:123], v[122:123], v[196:197]
	v_pk_add_f32 v[120:121], v[120:121], v[208:209]
	v_pk_add_f32 v[118:119], v[118:119], v[198:199]
	v_pk_add_f32 v[116:117], v[116:117], v[210:211]
	v_pk_add_f32 v[194:195], v[114:115], v[200:201]
	v_pk_add_f32 v[196:197], v[112:113], v[212:213]
	v_mul_f32_e32 v114, v125, v125
	v_mul_f32_e32 v115, v127, v127
	v_mul_f32_e32 v198, v121, v121
	v_mul_f32_e32 v199, v123, v123
	v_cvt_pk_bf16_f32 v112, v124, v125
	v_cvt_pk_bf16_f32 v113, v126, v127
	v_mul_f32_e32 v125, v117, v117
	v_mul_f32_e32 v127, v119, v119
	v_mul_f32_e32 v200, v197, v197
	v_mul_f32_e32 v201, v195, v195
	v_fmac_f32_e32 v114, v124, v124
	v_fmac_f32_e32 v115, v126, v126
	v_fmac_f32_e32 v198, v120, v120
	v_fmac_f32_e32 v199, v122, v122
	v_fmac_f32_e32 v125, v116, v116
	v_fmac_f32_e32 v127, v118, v118
	v_fmac_f32_e32 v200, v196, v196
	v_fmac_f32_e32 v201, v194, v194
	v_add_f32_e32 v114, v114, v115
	v_add_f32_e32 v115, v198, v199
	v_add_f32_e32 v124, v125, v127
	v_add_f32_e32 v125, v200, v201
	v_add_f32_e32 v114, v114, v115
	v_add_f32_e32 v115, v124, v125
	v_add_f32_e32 v124, v114, v115
	ds_bpermute_b32 v125, v193, v124
	v_cvt_pk_bf16_f32 v114, v120, v121
	v_cvt_pk_bf16_f32 v115, v122, v123
	global_store_dwordx4 v[204:205], v[112:115], off
	v_cvt_pk_bf16_f32 v116, v116, v117
	v_cvt_pk_bf16_f32 v117, v118, v119
	v_cvt_pk_bf16_f32 v118, v196, v197
	v_cvt_pk_bf16_f32 v119, v194, v195
	global_store_dwordx4 v[204:205], v[116:119], off offset:256
	s_waitcnt lgkmcnt(0)
	v_add_f32_e32 v113, v124, v125
	v_lshlrev_b32_e32 v112, 2, v214
	ds_bpermute_b32 v114, v112, v113
	s_and_saveexec_b64 s[4:5], s[6:7]
	s_cbranch_execz .LBB0_406
	v_lshlrev_b64 v[116:117], 6, v[172:173]
	v_lshl_add_u64 v[116:117], s[22:23], 0, v[116:117]
	v_lshl_add_u64 v[116:117], s[40:41], 2, v[116:117]
	s_lshl_b32 s10, s51, 2
	v_lshl_add_u64 v[116:117], v[116:117], 0, s[10:11]
	s_waitcnt lgkmcnt(0)
	v_add_f32_e32 v113, v113, v114
	global_store_dword v[116:117], v113, off

.LBB0_412:
	s_or_b64 exec, exec, s[4:5]
	v_add_u32_e32 v100, 0x80, v172
	v_ashrrev_i32_e32 v101, 31, v100
	v_lshlrev_b64 v[110:111], 11, v[100:101]
	s_waitcnt lgkmcnt(0)
	v_lshl_add_u64 v[64:65], v[170:171], 0, v[110:111]
	v_add_u32_e32 v96, 0x90, v172
	v_add_u32_e32 v92, 0xa0, v172
	v_add_u32_e32 v88, 0xb0, v172
	v_ashrrev_i32_e32 v97, 31, v96
	v_ashrrev_i32_e32 v93, 31, v92
	v_ashrrev_i32_e32 v89, 31, v88
	v_lshlrev_b64 v[98:99], 11, v[96:97]
	v_lshlrev_b64 v[94:95], 11, v[92:93]
	v_lshlrev_b64 v[90:91], 11, v[88:89]
	v_lshl_add_u64 v[64:65], v[170:171], 0, v[98:99]
	v_lshl_add_u64 v[66:67], v[170:171], 0, v[94:95]
	v_lshl_add_u64 v[114:115], v[170:171], 0, v[90:91]
	s_waitcnt vmcnt(15)
	v_lshlrev_b32_e32 v114, 16, v216
	v_and_b32_e32 v115, 0xffff0000, v216
	v_lshlrev_b32_e32 v102, 16, v217
	v_and_b32_e32 v103, 0xffff0000, v217
	v_lshlrev_b32_e32 v116, 16, v218
	v_and_b32_e32 v117, 0xffff0000, v218
	v_lshlrev_b32_e32 v104, 16, v219
	v_and_b32_e32 v105, 0xffff0000, v219
	s_waitcnt vmcnt(14)
	v_lshlrev_b32_e32 v118, 16, v220
	v_and_b32_e32 v119, 0xffff0000, v220
	v_lshlrev_b32_e32 v106, 16, v221
	v_and_b32_e32 v107, 0xffff0000, v221
	v_lshlrev_b32_e32 v120, 16, v222
	v_and_b32_e32 v121, 0xffff0000, v222
	v_lshlrev_b32_e32 v108, 16, v223
	v_and_b32_e32 v109, 0xffff0000, v223
	v_pk_add_f32 v[62:63], v[62:63], v[102:103]
	v_pk_add_f32 v[60:61], v[60:61], v[114:115]
	v_pk_add_f32 v[58:59], v[58:59], v[104:105]
	v_pk_add_f32 v[56:57], v[56:57], v[116:117]
	v_pk_add_f32 v[54:55], v[54:55], v[106:107]
	v_pk_add_f32 v[52:53], v[52:53], v[118:119]
	v_pk_add_f32 v[102:103], v[50:51], v[108:109]
	v_pk_add_f32 v[104:105], v[48:49], v[120:121]
	v_mul_f32_e32 v106, v61, v61
	v_mul_f32_e32 v107, v63, v63
	v_mul_f32_e32 v108, v57, v57
	v_mul_f32_e32 v109, v59, v59
	v_cvt_pk_bf16_f32 v48, v60, v61
	v_cvt_pk_bf16_f32 v49, v62, v63
	v_cvt_pk_bf16_f32 v50, v56, v57
	v_cvt_pk_bf16_f32 v51, v58, v59
	v_mul_f32_e32 v57, v53, v53
	v_mul_f32_e32 v59, v55, v55
	v_mul_f32_e32 v61, v105, v105
	v_mul_f32_e32 v63, v103, v103
	v_fmac_f32_e32 v106, v60, v60
	v_fmac_f32_e32 v107, v62, v62
	v_fmac_f32_e32 v108, v56, v56
	v_fmac_f32_e32 v109, v58, v58
	v_fmac_f32_e32 v57, v52, v52
	v_fmac_f32_e32 v59, v54, v54
	v_fmac_f32_e32 v61, v104, v104
	v_fmac_f32_e32 v63, v102, v102
	v_add_f32_e32 v56, v106, v107
	v_add_f32_e32 v58, v108, v109
	v_add_f32_e32 v57, v57, v59
	v_add_f32_e32 v59, v61, v63
	v_add_f32_e32 v56, v56, v58
	v_add_f32_e32 v57, v57, v59
	v_add_f32_e32 v58, v56, v57
	ds_bpermute_b32 v59, v193, v58
	v_lshl_add_u64 v[56:57], s[16:17], 0, v[110:111]
	v_lshl_add_u64 v[56:57], v[168:169], 1, v[56:57]
	global_store_dwordx4 v[56:57], v[48:51], off
	s_waitcnt lgkmcnt(0)
	s_nop 0
	v_add_f32_e32 v48, v58, v59
	ds_bpermute_b32 v49, v112, v48
	v_cvt_pk_bf16_f32 v50, v52, v53
	v_cvt_pk_bf16_f32 v51, v54, v55
	v_cvt_pk_bf16_f32 v52, v104, v105
	v_cvt_pk_bf16_f32 v53, v102, v103
	global_store_dwordx4 v[56:57], v[50:53], off offset:256
	s_and_saveexec_b64 s[4:5], s[6:7]
	s_cbranch_execz .LBB0_414
	v_lshlrev_b64 v[50:51], 6, v[100:101]
	v_lshl_add_u64 v[50:51], s[22:23], 0, v[50:51]
	v_lshl_add_u64 v[50:51], s[40:41], 2, v[50:51]
	s_lshl_b32 s10, s51, 2
	v_lshl_add_u64 v[50:51], v[50:51], 0, s[10:11]
	s_waitcnt lgkmcnt(0)
	v_add_f32_e32 v48, v48, v49
	global_store_dword v[50:51], v48, off
.LBB0_414:
	s_or_b64 exec, exec, s[4:5]
	s_waitcnt vmcnt(15)
	v_lshlrev_b32_e32 v48, 16, v224
	s_waitcnt lgkmcnt(0)
	v_and_b32_e32 v49, 0xffff0000, v224
	v_lshlrev_b32_e32 v50, 16, v225
	v_and_b32_e32 v51, 0xffff0000, v225
	v_lshlrev_b32_e32 v52, 16, v226
	v_and_b32_e32 v53, 0xffff0000, v226
	v_lshlrev_b32_e32 v54, 16, v227
	v_and_b32_e32 v55, 0xffff0000, v227
	v_pk_add_f32 v[46:47], v[46:47], v[50:51]
	v_pk_add_f32 v[44:45], v[44:45], v[48:49]
	v_pk_add_f32 v[48:49], v[42:43], v[54:55]
	v_pk_add_f32 v[42:43], v[40:41], v[52:53]
	v_mul_f32_e32 v40, v45, v45
	v_mul_f32_e32 v41, v47, v47
	v_fmac_f32_e32 v40, v44, v44
	v_fmac_f32_e32 v41, v46, v46
	v_add_f32_e32 v40, v40, v41
	v_mul_f32_e32 v41, v43, v43
	v_mul_f32_e32 v50, v49, v49
	v_fmac_f32_e32 v41, v42, v42
	v_fmac_f32_e32 v50, v48, v48
	v_add_f32_e32 v41, v41, v50
	v_add_f32_e32 v52, v40, v41
	v_cvt_pk_bf16_f32 v40, v44, v45
	v_cvt_pk_bf16_f32 v41, v46, v47
	s_waitcnt vmcnt(14)
	v_lshlrev_b32_e32 v44, 16, v228
	v_and_b32_e32 v45, 0xffff0000, v228
	v_lshlrev_b32_e32 v46, 16, v229
	v_and_b32_e32 v47, 0xffff0000, v229
	v_cvt_pk_bf16_f32 v42, v42, v43
	v_cvt_pk_bf16_f32 v43, v48, v49
	v_lshlrev_b32_e32 v48, 16, v230
	v_and_b32_e32 v49, 0xffff0000, v230
	v_pk_add_f32 v[38:39], v[38:39], v[46:47]
	v_pk_add_f32 v[36:37], v[36:37], v[44:45]
	v_lshlrev_b32_e32 v50, 16, v231
	v_and_b32_e32 v51, 0xffff0000, v231
	v_pk_add_f32 v[46:47], v[32:33], v[48:49]
	v_mul_f32_e32 v32, v37, v37
	v_mul_f32_e32 v33, v39, v39
	v_pk_add_f32 v[44:45], v[34:35], v[50:51]
	v_fmac_f32_e32 v32, v36, v36
	v_fmac_f32_e32 v33, v38, v38
	v_add_f32_e32 v32, v32, v33
	v_mul_f32_e32 v33, v47, v47
	v_mul_f32_e32 v34, v45, v45
	v_fmac_f32_e32 v33, v46, v46
	v_fmac_f32_e32 v34, v44, v44
	v_add_f32_e32 v33, v33, v34
	v_add_f32_e32 v32, v32, v33
	v_add_f32_e32 v35, v52, v32
	ds_bpermute_b32 v50, v193, v35
	v_lshl_add_u64 v[32:33], s[16:17], 0, v[98:99]
	v_lshl_add_u64 v[48:49], v[168:169], 1, v[32:33]
	global_store_dwordx4 v[48:49], v[40:43], off
	v_cvt_pk_bf16_f32 v34, v36, v37
	s_waitcnt lgkmcnt(0)
	v_add_f32_e32 v32, v35, v50
	ds_bpermute_b32 v33, v112, v32
	v_cvt_pk_bf16_f32 v35, v38, v39
	v_cvt_pk_bf16_f32 v36, v46, v47
	v_cvt_pk_bf16_f32 v37, v44, v45
	global_store_dwordx4 v[48:49], v[34:37], off offset:256
	s_and_saveexec_b64 s[4:5], s[6:7]
	s_cbranch_execz .LBB0_416
	v_lshlrev_b64 v[34:35], 6, v[96:97]
	v_lshl_add_u64 v[34:35], s[22:23], 0, v[34:35]
	v_lshl_add_u64 v[34:35], s[40:41], 2, v[34:35]
	s_lshl_b32 s10, s51, 2
	v_lshl_add_u64 v[34:35], v[34:35], 0, s[10:11]
	s_waitcnt lgkmcnt(0)
	v_add_f32_e32 v32, v32, v33
	global_store_dword v[34:35], v32, off
.LBB0_416:
	s_or_b64 exec, exec, s[4:5]
	s_waitcnt vmcnt(15)
	v_lshlrev_b32_e32 v32, 16, v232
	s_waitcnt lgkmcnt(0)
	v_and_b32_e32 v33, 0xffff0000, v232
	v_lshlrev_b32_e32 v34, 16, v233
	v_and_b32_e32 v35, 0xffff0000, v233
	v_lshlrev_b32_e32 v36, 16, v234
	v_and_b32_e32 v37, 0xffff0000, v234
	v_lshlrev_b32_e32 v38, 16, v235
	v_and_b32_e32 v39, 0xffff0000, v235
	v_pk_add_f32 v[30:31], v[30:31], v[34:35]
	v_pk_add_f32 v[28:29], v[28:29], v[32:33]
	v_pk_add_f32 v[32:33], v[26:27], v[38:39]
	v_pk_add_f32 v[26:27], v[24:25], v[36:37]
	v_mul_f32_e32 v24, v29, v29
	v_mul_f32_e32 v25, v31, v31
	v_fmac_f32_e32 v24, v28, v28
	v_fmac_f32_e32 v25, v30, v30
	v_add_f32_e32 v24, v24, v25
	v_mul_f32_e32 v25, v27, v27
	v_mul_f32_e32 v34, v33, v33
	v_fmac_f32_e32 v25, v26, v26
	v_fmac_f32_e32 v34, v32, v32
	v_add_f32_e32 v25, v25, v34
	v_add_f32_e32 v36, v24, v25
	v_cvt_pk_bf16_f32 v24, v28, v29
	v_cvt_pk_bf16_f32 v25, v30, v31
	s_waitcnt vmcnt(14)
	v_lshlrev_b32_e32 v28, 16, v236
	v_and_b32_e32 v29, 0xffff0000, v236
	v_lshlrev_b32_e32 v30, 16, v237
	v_and_b32_e32 v31, 0xffff0000, v237
	v_cvt_pk_bf16_f32 v26, v26, v27
	v_cvt_pk_bf16_f32 v27, v32, v33
	v_lshlrev_b32_e32 v32, 16, v238
	v_and_b32_e32 v33, 0xffff0000, v238
	v_pk_add_f32 v[22:23], v[22:23], v[30:31]
	v_pk_add_f32 v[20:21], v[20:21], v[28:29]
	v_lshlrev_b32_e32 v34, 16, v239
	v_and_b32_e32 v35, 0xffff0000, v239
	v_pk_add_f32 v[30:31], v[16:17], v[32:33]
	v_mul_f32_e32 v16, v21, v21
	v_mul_f32_e32 v17, v23, v23
	v_pk_add_f32 v[28:29], v[18:19], v[34:35]
	v_fmac_f32_e32 v16, v20, v20
	v_fmac_f32_e32 v17, v22, v22
	v_add_f32_e32 v16, v16, v17
	v_mul_f32_e32 v17, v31, v31
	v_mul_f32_e32 v18, v29, v29
	v_fmac_f32_e32 v17, v30, v30
	v_fmac_f32_e32 v18, v28, v28
	v_add_f32_e32 v17, v17, v18
	v_add_f32_e32 v16, v16, v17
	v_add_f32_e32 v19, v36, v16
	ds_bpermute_b32 v34, v193, v19
	v_lshl_add_u64 v[16:17], s[16:17], 0, v[94:95]
	v_lshl_add_u64 v[32:33], v[168:169], 1, v[16:17]
	global_store_dwordx4 v[32:33], v[24:27], off
	v_cvt_pk_bf16_f32 v18, v20, v21
	s_waitcnt lgkmcnt(0)
	v_add_f32_e32 v16, v19, v34
	ds_bpermute_b32 v17, v112, v16
	v_cvt_pk_bf16_f32 v19, v22, v23
	v_cvt_pk_bf16_f32 v20, v30, v31
	v_cvt_pk_bf16_f32 v21, v28, v29
	global_store_dwordx4 v[32:33], v[18:21], off offset:256
	s_and_saveexec_b64 s[4:5], s[6:7]
	s_cbranch_execz .LBB0_418
	v_lshlrev_b64 v[18:19], 6, v[92:93]
	v_lshl_add_u64 v[18:19], s[22:23], 0, v[18:19]
	v_lshl_add_u64 v[18:19], s[40:41], 2, v[18:19]
	s_lshl_b32 s10, s51, 2
	v_lshl_add_u64 v[18:19], v[18:19], 0, s[10:11]
	s_waitcnt lgkmcnt(0)
	v_add_f32_e32 v16, v16, v17
	global_store_dword v[18:19], v16, off
.LBB0_418:
	s_or_b64 exec, exec, s[4:5]
	s_waitcnt vmcnt(15)
	v_lshlrev_b32_e32 v16, 16, v240
	s_waitcnt lgkmcnt(0)
	v_and_b32_e32 v17, 0xffff0000, v240
	v_lshlrev_b32_e32 v18, 16, v241
	v_and_b32_e32 v19, 0xffff0000, v241
	v_lshlrev_b32_e32 v20, 16, v242
	v_and_b32_e32 v21, 0xffff0000, v242
	v_lshlrev_b32_e32 v22, 16, v243
	v_and_b32_e32 v23, 0xffff0000, v243
	v_pk_add_f32 v[14:15], v[14:15], v[18:19]
	v_pk_add_f32 v[12:13], v[12:13], v[16:17]
	v_pk_add_f32 v[16:17], v[10:11], v[22:23]
	v_pk_add_f32 v[10:11], v[8:9], v[20:21]
	v_mul_f32_e32 v8, v13, v13
	v_mul_f32_e32 v9, v15, v15
	v_fmac_f32_e32 v8, v12, v12
	v_fmac_f32_e32 v9, v14, v14
	v_add_f32_e32 v8, v8, v9
	v_mul_f32_e32 v9, v11, v11
	v_mul_f32_e32 v18, v17, v17
	v_fmac_f32_e32 v9, v10, v10
	v_fmac_f32_e32 v18, v16, v16
	v_add_f32_e32 v9, v9, v18
	v_add_f32_e32 v20, v8, v9
	v_cvt_pk_bf16_f32 v8, v12, v13
	v_cvt_pk_bf16_f32 v9, v14, v15
	s_waitcnt vmcnt(14)
	v_lshlrev_b32_e32 v12, 16, v244
	v_and_b32_e32 v13, 0xffff0000, v244
	v_lshlrev_b32_e32 v14, 16, v245
	v_and_b32_e32 v15, 0xffff0000, v245
	v_cvt_pk_bf16_f32 v10, v10, v11
	v_cvt_pk_bf16_f32 v11, v16, v17
	v_lshlrev_b32_e32 v16, 16, v246
	v_and_b32_e32 v17, 0xffff0000, v246
	v_pk_add_f32 v[6:7], v[6:7], v[14:15]
	v_pk_add_f32 v[4:5], v[4:5], v[12:13]
	v_lshlrev_b32_e32 v18, 16, v247
	v_and_b32_e32 v19, 0xffff0000, v247
	v_pk_add_f32 v[14:15], v[0:1], v[16:17]
	v_mul_f32_e32 v0, v5, v5
	v_mul_f32_e32 v1, v7, v7
	v_pk_add_f32 v[12:13], v[2:3], v[18:19]
	v_fmac_f32_e32 v0, v4, v4
	v_fmac_f32_e32 v1, v6, v6
	v_add_f32_e32 v0, v0, v1
	v_mul_f32_e32 v1, v15, v15
	v_mul_f32_e32 v2, v13, v13
	v_fmac_f32_e32 v1, v14, v14
	v_fmac_f32_e32 v2, v12, v12
	v_add_f32_e32 v1, v1, v2
	v_add_f32_e32 v0, v0, v1
	v_add_f32_e32 v3, v20, v0
	ds_bpermute_b32 v18, v193, v3
	v_lshl_add_u64 v[0:1], s[16:17], 0, v[90:91]
	v_lshl_add_u64 v[16:17], v[168:169], 1, v[0:1]
	global_store_dwordx4 v[16:17], v[8:11], off
	v_cvt_pk_bf16_f32 v2, v4, v5
	s_waitcnt lgkmcnt(0)
	v_add_f32_e32 v0, v3, v18
	ds_bpermute_b32 v1, v112, v0
	v_cvt_pk_bf16_f32 v3, v6, v7
	v_cvt_pk_bf16_f32 v4, v14, v15
	v_cvt_pk_bf16_f32 v5, v12, v13
	global_store_dwordx4 v[16:17], v[2:5], off offset:256
	s_and_saveexec_b64 s[4:5], s[6:7]
	s_cbranch_execz .LBB0_420
	v_lshlrev_b64 v[2:3], 6, v[88:89]
	v_lshl_add_u64 v[2:3], s[22:23], 0, v[2:3]
	v_lshl_add_u64 v[2:3], s[40:41], 2, v[2:3]
	s_lshl_b32 s10, s51, 2
	v_lshl_add_u64 v[2:3], v[2:3], 0, s[10:11]
	s_waitcnt lgkmcnt(0)
	v_add_f32_e32 v0, v0, v1
	global_store_dword v[2:3], v0, off

.LBB0_562:
	v_lshl_or_b32 v168, s12, 8, v188
	v_lshl_add_u32 v172, s54, 8, v186
	v_ashrrev_i32_e32 v169, 31, v168
	v_lshlrev_b64 v[204:205], 1, v[168:169]
	v_ashrrev_i32_e32 v173, 31, v172
	v_lshl_add_u64 v[170:171], s[26:27], 0, v[204:205]
	v_lshlrev_b64 v[206:207], 11, v[172:173]
	v_lshl_add_u64 v[128:129], v[170:171], 0, v[206:207]
	global_load_dwordx4 v[194:197], v[128:129], off
	global_load_dwordx4 v[198:201], v[128:129], off offset:256
	v_or_b32_e32 v182, 16, v172
	v_or_b32_e32 v178, 32, v172
	v_or_b32_e32 v174, 48, v172
	v_ashrrev_i32_e32 v183, 31, v182
	v_ashrrev_i32_e32 v179, 31, v178
	v_ashrrev_i32_e32 v175, 31, v174
	v_lshlrev_b64 v[184:185], 11, v[182:183]
	v_lshlrev_b64 v[180:181], 11, v[178:179]
	v_lshlrev_b64 v[176:177], 11, v[174:175]
	v_lshl_add_u64 v[128:129], v[170:171], 0, v[184:185]
	v_lshl_add_u64 v[130:131], v[170:171], 0, v[180:181]
	v_lshl_add_u64 v[208:209], v[170:171], 0, v[176:177]
	global_load_dwordx4 v[148:151], v[128:129], off
	global_load_dwordx4 v[144:147], v[128:129], off offset:256
	global_load_dwordx4 v[140:143], v[130:131], off
	global_load_dwordx4 v[136:139], v[130:131], off offset:256
	global_load_dwordx4 v[132:135], v[208:209], off
	s_nop 0
	global_load_dwordx4 v[128:131], v[208:209], off offset:256
	v_add_u32_e32 v248, 0x80, v172
	v_ashrrev_i32_e32 v249, 31, v248
	v_lshlrev_b64 v[248:249], 11, v[248:249]
	v_lshl_add_u64 v[248:249], v[170:171], 0, v[248:249]
	global_load_dwordx4 v[216:219], v[248:249], off
	global_load_dwordx4 v[220:223], v[248:249], off offset:256
	v_add_u32_e32 v250, 0x90, v172
	v_ashrrev_i32_e32 v251, 31, v250
	v_lshlrev_b64 v[250:251], 11, v[250:251]
	v_lshl_add_u64 v[250:251], v[170:171], 0, v[250:251]
	global_load_dwordx4 v[224:227], v[250:251], off
	global_load_dwordx4 v[228:231], v[250:251], off offset:256
	v_add_u32_e32 v252, 0xa0, v172
	v_ashrrev_i32_e32 v253, 31, v252
	v_lshlrev_b64 v[252:253], 11, v[252:253]
	v_lshl_add_u64 v[252:253], v[170:171], 0, v[252:253]
	global_load_dwordx4 v[232:235], v[252:253], off
	global_load_dwordx4 v[236:239], v[252:253], off offset:256
	v_add_u32_e32 v248, 0xb0, v172
	v_ashrrev_i32_e32 v249, 31, v248
	v_lshlrev_b64 v[248:249], 11, v[248:249]
	v_lshl_add_u64 v[248:249], v[170:171], 0, v[248:249]
	global_load_dwordx4 v[240:243], v[248:249], off
	global_load_dwordx4 v[244:247], v[248:249], off offset:256
	v_and_b32_e32 v208, 64, v192
	v_xor_b32_e32 v193, 16, v192
	v_add_u32_e32 v208, 64, v208
	v_xor_b32_e32 v209, 32, v192
	v_cmp_lt_i32_e32 vcc, v193, v208
	v_lshl_add_u64 v[206:207], s[26:27], 0, v[206:207]
	v_lshl_add_u64 v[204:205], v[206:207], 0, v[204:205]
	v_cndmask_b32_e32 v193, v192, v193, vcc
	v_cmp_lt_i32_e32 vcc, v209, v208
	v_lshlrev_b32_e32 v193, 2, v193
	s_lshl_b32 s38, s12, 2
	v_cndmask_b32_e32 v214, v192, v209, vcc
	s_ashr_i32 s39, s38, 31
	s_waitcnt vmcnt(8)
	v_lshlrev_b32_e32 v206, 16, v194
	v_and_b32_e32 v207, 0xffff0000, v194
	v_lshlrev_b32_e32 v194, 16, v195
	v_and_b32_e32 v195, 0xffff0000, v195
	v_lshlrev_b32_e32 v208, 16, v196
	v_and_b32_e32 v209, 0xffff0000, v196
	v_lshlrev_b32_e32 v196, 16, v197
	v_and_b32_e32 v197, 0xffff0000, v197
	v_lshlrev_b32_e32 v210, 16, v198
	v_and_b32_e32 v211, 0xffff0000, v198
	v_lshlrev_b32_e32 v198, 16, v199
	v_and_b32_e32 v199, 0xffff0000, v199
	v_lshlrev_b32_e32 v212, 16, v200
	v_and_b32_e32 v213, 0xffff0000, v200
	v_lshlrev_b32_e32 v200, 16, v201
	v_and_b32_e32 v201, 0xffff0000, v201
	v_pk_add_f32 v[126:127], v[126:127], v[194:195]
	v_pk_add_f32 v[124:125], v[124:125], v[206:207]
	v_pk_add_f32 v[122:123], v[122:123], v[196:197]
	v_pk_add_f32 v[120:121], v[120:121], v[208:209]
	v_pk_add_f32 v[118:119], v[118:119], v[198:199]
	v_pk_add_f32 v[116:117], v[116:117], v[210:211]
	v_pk_add_f32 v[194:195], v[114:115], v[200:201]
	v_pk_add_f32 v[196:197], v[112:113], v[212:213]
	v_mul_f32_e32 v114, v125, v125
	v_mul_f32_e32 v115, v127, v127
	v_mul_f32_e32 v198, v121, v121
	v_mul_f32_e32 v199, v123, v123
	v_cvt_pk_bf16_f32 v112, v124, v125
	v_cvt_pk_bf16_f32 v113, v126, v127
	v_mul_f32_e32 v125, v117, v117
	v_mul_f32_e32 v127, v119, v119
	v_mul_f32_e32 v200, v197, v197
	v_mul_f32_e32 v201, v195, v195
	v_fmac_f32_e32 v114, v124, v124
	v_fmac_f32_e32 v115, v126, v126
	v_fmac_f32_e32 v198, v120, v120
	v_fmac_f32_e32 v199, v122, v122
	v_fmac_f32_e32 v125, v116, v116
	v_fmac_f32_e32 v127, v118, v118
	v_fmac_f32_e32 v200, v196, v196
	v_fmac_f32_e32 v201, v194, v194
	v_add_f32_e32 v114, v114, v115
	v_add_f32_e32 v115, v198, v199
	v_add_f32_e32 v124, v125, v127
	v_add_f32_e32 v125, v200, v201
	v_add_f32_e32 v114, v114, v115
	v_add_f32_e32 v115, v124, v125
	v_add_f32_e32 v124, v114, v115
	ds_bpermute_b32 v125, v193, v124
	v_cvt_pk_bf16_f32 v114, v120, v121
	v_cvt_pk_bf16_f32 v115, v122, v123
	global_store_dwordx4 v[204:205], v[112:115], off
	v_cvt_pk_bf16_f32 v116, v116, v117
	v_cvt_pk_bf16_f32 v117, v118, v119
	v_cvt_pk_bf16_f32 v118, v196, v197
	v_cvt_pk_bf16_f32 v119, v194, v195
	global_store_dwordx4 v[204:205], v[116:119], off offset:256
	s_waitcnt lgkmcnt(0)
	v_add_f32_e32 v113, v124, v125
	v_lshlrev_b32_e32 v112, 2, v214
	ds_bpermute_b32 v114, v112, v113
	s_and_saveexec_b64 s[4:5], s[6:7]
	s_cbranch_execz .LBB0_564
	v_lshlrev_b64 v[116:117], 6, v[172:173]
	v_lshl_add_u64 v[116:117], s[28:29], 0, v[116:117]
	v_lshl_add_u64 v[116:117], s[38:39], 2, v[116:117]
	s_lshl_b32 s12, s47, 2
	v_lshl_add_u64 v[116:117], v[116:117], 0, s[12:13]
	s_waitcnt lgkmcnt(0)
	v_add_f32_e32 v113, v113, v114
	global_store_dword v[116:117], v113, off

.LBB0_570:
	s_or_b64 exec, exec, s[4:5]
	v_add_u32_e32 v100, 0x80, v172
	v_ashrrev_i32_e32 v101, 31, v100
	v_lshlrev_b64 v[110:111], 11, v[100:101]
	s_waitcnt lgkmcnt(0)
	v_lshl_add_u64 v[64:65], v[170:171], 0, v[110:111]
	v_add_u32_e32 v96, 0x90, v172
	v_add_u32_e32 v92, 0xa0, v172
	v_add_u32_e32 v88, 0xb0, v172
	v_ashrrev_i32_e32 v97, 31, v96
	v_ashrrev_i32_e32 v93, 31, v92
	v_ashrrev_i32_e32 v89, 31, v88
	v_lshlrev_b64 v[98:99], 11, v[96:97]
	v_lshlrev_b64 v[94:95], 11, v[92:93]
	v_lshlrev_b64 v[90:91], 11, v[88:89]
	v_lshl_add_u64 v[64:65], v[170:171], 0, v[98:99]
	v_lshl_add_u64 v[66:67], v[170:171], 0, v[94:95]
	v_lshl_add_u64 v[114:115], v[170:171], 0, v[90:91]
	s_waitcnt vmcnt(15)
	v_lshlrev_b32_e32 v114, 16, v216
	v_and_b32_e32 v115, 0xffff0000, v216
	v_lshlrev_b32_e32 v102, 16, v217
	v_and_b32_e32 v103, 0xffff0000, v217
	v_lshlrev_b32_e32 v116, 16, v218
	v_and_b32_e32 v117, 0xffff0000, v218
	v_lshlrev_b32_e32 v104, 16, v219
	v_and_b32_e32 v105, 0xffff0000, v219
	s_waitcnt vmcnt(14)
	v_lshlrev_b32_e32 v118, 16, v220
	v_and_b32_e32 v119, 0xffff0000, v220
	v_lshlrev_b32_e32 v106, 16, v221
	v_and_b32_e32 v107, 0xffff0000, v221
	v_lshlrev_b32_e32 v120, 16, v222
	v_and_b32_e32 v121, 0xffff0000, v222
	v_lshlrev_b32_e32 v108, 16, v223
	v_and_b32_e32 v109, 0xffff0000, v223
	v_pk_add_f32 v[62:63], v[62:63], v[102:103]
	v_pk_add_f32 v[60:61], v[60:61], v[114:115]
	v_pk_add_f32 v[58:59], v[58:59], v[104:105]
	v_pk_add_f32 v[56:57], v[56:57], v[116:117]
	v_pk_add_f32 v[54:55], v[54:55], v[106:107]
	v_pk_add_f32 v[52:53], v[52:53], v[118:119]
	v_pk_add_f32 v[102:103], v[50:51], v[108:109]
	v_pk_add_f32 v[104:105], v[48:49], v[120:121]
	v_mul_f32_e32 v106, v61, v61
	v_mul_f32_e32 v107, v63, v63
	v_mul_f32_e32 v108, v57, v57
	v_mul_f32_e32 v109, v59, v59
	v_cvt_pk_bf16_f32 v48, v60, v61
	v_cvt_pk_bf16_f32 v49, v62, v63
	v_cvt_pk_bf16_f32 v50, v56, v57
	v_cvt_pk_bf16_f32 v51, v58, v59
	v_mul_f32_e32 v57, v53, v53
	v_mul_f32_e32 v59, v55, v55
	v_mul_f32_e32 v61, v105, v105
	v_mul_f32_e32 v63, v103, v103
	v_fmac_f32_e32 v106, v60, v60
	v_fmac_f32_e32 v107, v62, v62
	v_fmac_f32_e32 v108, v56, v56
	v_fmac_f32_e32 v109, v58, v58
	v_fmac_f32_e32 v57, v52, v52
	v_fmac_f32_e32 v59, v54, v54
	v_fmac_f32_e32 v61, v104, v104
	v_fmac_f32_e32 v63, v102, v102
	v_add_f32_e32 v56, v106, v107
	v_add_f32_e32 v58, v108, v109
	v_add_f32_e32 v57, v57, v59
	v_add_f32_e32 v59, v61, v63
	v_add_f32_e32 v56, v56, v58
	v_add_f32_e32 v57, v57, v59
	v_add_f32_e32 v58, v56, v57
	ds_bpermute_b32 v59, v193, v58
	v_lshl_add_u64 v[56:57], s[26:27], 0, v[110:111]
	v_lshl_add_u64 v[56:57], v[168:169], 1, v[56:57]
	global_store_dwordx4 v[56:57], v[48:51], off
	s_waitcnt lgkmcnt(0)
	s_nop 0
	v_add_f32_e32 v48, v58, v59
	ds_bpermute_b32 v49, v112, v48
	v_cvt_pk_bf16_f32 v50, v52, v53
	v_cvt_pk_bf16_f32 v51, v54, v55
	v_cvt_pk_bf16_f32 v52, v104, v105
	v_cvt_pk_bf16_f32 v53, v102, v103
	global_store_dwordx4 v[56:57], v[50:53], off offset:256
	s_and_saveexec_b64 s[4:5], s[6:7]
	s_cbranch_execz .LBB0_572
	v_lshlrev_b64 v[50:51], 6, v[100:101]
	v_lshl_add_u64 v[50:51], s[28:29], 0, v[50:51]
	v_lshl_add_u64 v[50:51], s[38:39], 2, v[50:51]
	s_lshl_b32 s12, s47, 2
	v_lshl_add_u64 v[50:51], v[50:51], 0, s[12:13]
	s_waitcnt lgkmcnt(0)
	v_add_f32_e32 v48, v48, v49
	global_store_dword v[50:51], v48, off
.LBB0_572:
	s_or_b64 exec, exec, s[4:5]
	s_waitcnt vmcnt(15)
	v_lshlrev_b32_e32 v48, 16, v224
	s_waitcnt lgkmcnt(0)
	v_and_b32_e32 v49, 0xffff0000, v224
	v_lshlrev_b32_e32 v50, 16, v225
	v_and_b32_e32 v51, 0xffff0000, v225
	v_lshlrev_b32_e32 v52, 16, v226
	v_and_b32_e32 v53, 0xffff0000, v226
	v_lshlrev_b32_e32 v54, 16, v227
	v_and_b32_e32 v55, 0xffff0000, v227
	v_pk_add_f32 v[46:47], v[46:47], v[50:51]
	v_pk_add_f32 v[44:45], v[44:45], v[48:49]
	v_pk_add_f32 v[48:49], v[42:43], v[54:55]
	v_pk_add_f32 v[42:43], v[40:41], v[52:53]
	v_mul_f32_e32 v40, v45, v45
	v_mul_f32_e32 v41, v47, v47
	v_fmac_f32_e32 v40, v44, v44
	v_fmac_f32_e32 v41, v46, v46
	v_add_f32_e32 v40, v40, v41
	v_mul_f32_e32 v41, v43, v43
	v_mul_f32_e32 v50, v49, v49
	v_fmac_f32_e32 v41, v42, v42
	v_fmac_f32_e32 v50, v48, v48
	v_add_f32_e32 v41, v41, v50
	v_add_f32_e32 v52, v40, v41
	v_cvt_pk_bf16_f32 v40, v44, v45
	v_cvt_pk_bf16_f32 v41, v46, v47
	s_waitcnt vmcnt(14)
	v_lshlrev_b32_e32 v44, 16, v228
	v_and_b32_e32 v45, 0xffff0000, v228
	v_lshlrev_b32_e32 v46, 16, v229
	v_and_b32_e32 v47, 0xffff0000, v229
	v_cvt_pk_bf16_f32 v42, v42, v43
	v_cvt_pk_bf16_f32 v43, v48, v49
	v_lshlrev_b32_e32 v48, 16, v230
	v_and_b32_e32 v49, 0xffff0000, v230
	v_pk_add_f32 v[38:39], v[38:39], v[46:47]
	v_pk_add_f32 v[36:37], v[36:37], v[44:45]
	v_lshlrev_b32_e32 v50, 16, v231
	v_and_b32_e32 v51, 0xffff0000, v231
	v_pk_add_f32 v[46:47], v[32:33], v[48:49]
	v_mul_f32_e32 v32, v37, v37
	v_mul_f32_e32 v33, v39, v39
	v_pk_add_f32 v[44:45], v[34:35], v[50:51]
	v_fmac_f32_e32 v32, v36, v36
	v_fmac_f32_e32 v33, v38, v38
	v_add_f32_e32 v32, v32, v33
	v_mul_f32_e32 v33, v47, v47
	v_mul_f32_e32 v34, v45, v45
	v_fmac_f32_e32 v33, v46, v46
	v_fmac_f32_e32 v34, v44, v44
	v_add_f32_e32 v33, v33, v34
	v_add_f32_e32 v32, v32, v33
	v_add_f32_e32 v35, v52, v32
	ds_bpermute_b32 v50, v193, v35
	v_lshl_add_u64 v[32:33], s[26:27], 0, v[98:99]
	v_lshl_add_u64 v[48:49], v[168:169], 1, v[32:33]
	global_store_dwordx4 v[48:49], v[40:43], off
	v_cvt_pk_bf16_f32 v34, v36, v37
	s_waitcnt lgkmcnt(0)
	v_add_f32_e32 v32, v35, v50
	ds_bpermute_b32 v33, v112, v32
	v_cvt_pk_bf16_f32 v35, v38, v39
	v_cvt_pk_bf16_f32 v36, v46, v47
	v_cvt_pk_bf16_f32 v37, v44, v45
	global_store_dwordx4 v[48:49], v[34:37], off offset:256
	s_and_saveexec_b64 s[4:5], s[6:7]
	s_cbranch_execz .LBB0_574
	v_lshlrev_b64 v[34:35], 6, v[96:97]
	v_lshl_add_u64 v[34:35], s[28:29], 0, v[34:35]
	v_lshl_add_u64 v[34:35], s[38:39], 2, v[34:35]
	s_lshl_b32 s12, s47, 2
	v_lshl_add_u64 v[34:35], v[34:35], 0, s[12:13]
	s_waitcnt lgkmcnt(0)
	v_add_f32_e32 v32, v32, v33
	global_store_dword v[34:35], v32, off
.LBB0_574:
	s_or_b64 exec, exec, s[4:5]
	s_waitcnt vmcnt(15)
	v_lshlrev_b32_e32 v32, 16, v232
	s_waitcnt lgkmcnt(0)
	v_and_b32_e32 v33, 0xffff0000, v232
	v_lshlrev_b32_e32 v34, 16, v233
	v_and_b32_e32 v35, 0xffff0000, v233
	v_lshlrev_b32_e32 v36, 16, v234
	v_and_b32_e32 v37, 0xffff0000, v234
	v_lshlrev_b32_e32 v38, 16, v235
	v_and_b32_e32 v39, 0xffff0000, v235
	v_pk_add_f32 v[30:31], v[30:31], v[34:35]
	v_pk_add_f32 v[28:29], v[28:29], v[32:33]
	v_pk_add_f32 v[32:33], v[26:27], v[38:39]
	v_pk_add_f32 v[26:27], v[24:25], v[36:37]
	v_mul_f32_e32 v24, v29, v29
	v_mul_f32_e32 v25, v31, v31
	v_fmac_f32_e32 v24, v28, v28
	v_fmac_f32_e32 v25, v30, v30
	v_add_f32_e32 v24, v24, v25
	v_mul_f32_e32 v25, v27, v27
	v_mul_f32_e32 v34, v33, v33
	v_fmac_f32_e32 v25, v26, v26
	v_fmac_f32_e32 v34, v32, v32
	v_add_f32_e32 v25, v25, v34
	v_add_f32_e32 v36, v24, v25
	v_cvt_pk_bf16_f32 v24, v28, v29
	v_cvt_pk_bf16_f32 v25, v30, v31
	s_waitcnt vmcnt(14)
	v_lshlrev_b32_e32 v28, 16, v236
	v_and_b32_e32 v29, 0xffff0000, v236
	v_lshlrev_b32_e32 v30, 16, v237
	v_and_b32_e32 v31, 0xffff0000, v237
	v_cvt_pk_bf16_f32 v26, v26, v27
	v_cvt_pk_bf16_f32 v27, v32, v33
	v_lshlrev_b32_e32 v32, 16, v238
	v_and_b32_e32 v33, 0xffff0000, v238
	v_pk_add_f32 v[22:23], v[22:23], v[30:31]
	v_pk_add_f32 v[20:21], v[20:21], v[28:29]
	v_lshlrev_b32_e32 v34, 16, v239
	v_and_b32_e32 v35, 0xffff0000, v239
	v_pk_add_f32 v[30:31], v[16:17], v[32:33]
	v_mul_f32_e32 v16, v21, v21
	v_mul_f32_e32 v17, v23, v23
	v_pk_add_f32 v[28:29], v[18:19], v[34:35]
	v_fmac_f32_e32 v16, v20, v20
	v_fmac_f32_e32 v17, v22, v22
	v_add_f32_e32 v16, v16, v17
	v_mul_f32_e32 v17, v31, v31
	v_mul_f32_e32 v18, v29, v29
	v_fmac_f32_e32 v17, v30, v30
	v_fmac_f32_e32 v18, v28, v28
	v_add_f32_e32 v17, v17, v18
	v_add_f32_e32 v16, v16, v17
	v_add_f32_e32 v19, v36, v16
	ds_bpermute_b32 v34, v193, v19
	v_lshl_add_u64 v[16:17], s[26:27], 0, v[94:95]
	v_lshl_add_u64 v[32:33], v[168:169], 1, v[16:17]
	global_store_dwordx4 v[32:33], v[24:27], off
	v_cvt_pk_bf16_f32 v18, v20, v21
	s_waitcnt lgkmcnt(0)
	v_add_f32_e32 v16, v19, v34
	ds_bpermute_b32 v17, v112, v16
	v_cvt_pk_bf16_f32 v19, v22, v23
	v_cvt_pk_bf16_f32 v20, v30, v31
	v_cvt_pk_bf16_f32 v21, v28, v29
	global_store_dwordx4 v[32:33], v[18:21], off offset:256
	s_and_saveexec_b64 s[4:5], s[6:7]
	s_cbranch_execz .LBB0_576
	v_lshlrev_b64 v[18:19], 6, v[92:93]
	v_lshl_add_u64 v[18:19], s[28:29], 0, v[18:19]
	v_lshl_add_u64 v[18:19], s[38:39], 2, v[18:19]
	s_lshl_b32 s12, s47, 2
	v_lshl_add_u64 v[18:19], v[18:19], 0, s[12:13]
	s_waitcnt lgkmcnt(0)
	v_add_f32_e32 v16, v16, v17
	global_store_dword v[18:19], v16, off
.LBB0_576:
	s_or_b64 exec, exec, s[4:5]
	s_waitcnt vmcnt(15)
	v_lshlrev_b32_e32 v16, 16, v240
	s_waitcnt lgkmcnt(0)
	v_and_b32_e32 v17, 0xffff0000, v240
	v_lshlrev_b32_e32 v18, 16, v241
	v_and_b32_e32 v19, 0xffff0000, v241
	v_lshlrev_b32_e32 v20, 16, v242
	v_and_b32_e32 v21, 0xffff0000, v242
	v_lshlrev_b32_e32 v22, 16, v243
	v_and_b32_e32 v23, 0xffff0000, v243
	v_pk_add_f32 v[14:15], v[14:15], v[18:19]
	v_pk_add_f32 v[12:13], v[12:13], v[16:17]
	v_pk_add_f32 v[16:17], v[10:11], v[22:23]
	v_pk_add_f32 v[10:11], v[8:9], v[20:21]
	v_mul_f32_e32 v8, v13, v13
	v_mul_f32_e32 v9, v15, v15
	v_fmac_f32_e32 v8, v12, v12
	v_fmac_f32_e32 v9, v14, v14
	v_add_f32_e32 v8, v8, v9
	v_mul_f32_e32 v9, v11, v11
	v_mul_f32_e32 v18, v17, v17
	v_fmac_f32_e32 v9, v10, v10
	v_fmac_f32_e32 v18, v16, v16
	v_add_f32_e32 v9, v9, v18
	v_add_f32_e32 v20, v8, v9
	v_cvt_pk_bf16_f32 v8, v12, v13
	v_cvt_pk_bf16_f32 v9, v14, v15
	s_waitcnt vmcnt(14)
	v_lshlrev_b32_e32 v12, 16, v244
	v_and_b32_e32 v13, 0xffff0000, v244
	v_lshlrev_b32_e32 v14, 16, v245
	v_and_b32_e32 v15, 0xffff0000, v245
	v_cvt_pk_bf16_f32 v10, v10, v11
	v_cvt_pk_bf16_f32 v11, v16, v17
	v_lshlrev_b32_e32 v16, 16, v246
	v_and_b32_e32 v17, 0xffff0000, v246
	v_pk_add_f32 v[6:7], v[6:7], v[14:15]
	v_pk_add_f32 v[4:5], v[4:5], v[12:13]
	v_lshlrev_b32_e32 v18, 16, v247
	v_and_b32_e32 v19, 0xffff0000, v247
	v_pk_add_f32 v[14:15], v[0:1], v[16:17]
	v_mul_f32_e32 v0, v5, v5
	v_mul_f32_e32 v1, v7, v7
	v_pk_add_f32 v[12:13], v[2:3], v[18:19]
	v_fmac_f32_e32 v0, v4, v4
	v_fmac_f32_e32 v1, v6, v6
	v_add_f32_e32 v0, v0, v1
	v_mul_f32_e32 v1, v15, v15
	v_mul_f32_e32 v2, v13, v13
	v_fmac_f32_e32 v1, v14, v14
	v_fmac_f32_e32 v2, v12, v12
	v_add_f32_e32 v1, v1, v2
	v_add_f32_e32 v0, v0, v1
	v_add_f32_e32 v3, v20, v0
	ds_bpermute_b32 v18, v193, v3
	v_lshl_add_u64 v[0:1], s[26:27], 0, v[90:91]
	v_lshl_add_u64 v[16:17], v[168:169], 1, v[0:1]
	global_store_dwordx4 v[16:17], v[8:11], off
	v_cvt_pk_bf16_f32 v2, v4, v5
	s_waitcnt lgkmcnt(0)
	v_add_f32_e32 v0, v3, v18
	ds_bpermute_b32 v1, v112, v0
	v_cvt_pk_bf16_f32 v3, v6, v7
	v_cvt_pk_bf16_f32 v4, v14, v15
	v_cvt_pk_bf16_f32 v5, v12, v13
	global_store_dwordx4 v[16:17], v[2:5], off offset:256
	s_and_saveexec_b64 s[4:5], s[6:7]
	s_cbranch_execz .LBB0_578
	v_lshlrev_b64 v[2:3], 6, v[88:89]
	v_lshl_add_u64 v[2:3], s[28:29], 0, v[2:3]
	v_lshl_add_u64 v[2:3], s[38:39], 2, v[2:3]
	s_lshl_b32 s12, s47, 2
	v_lshl_add_u64 v[2:3], v[2:3], 0, s[12:13]
	s_waitcnt lgkmcnt(0)
	v_add_f32_e32 v0, v0, v1
	global_store_dword v[2:3], v0, off

.LBB0_969:
	v_lshl_or_b32 v168, s10, 8, v188
	v_lshl_add_u32 v172, s40, 8, v186
	v_ashrrev_i32_e32 v169, 31, v168
	v_lshlrev_b64 v[204:205], 1, v[168:169]
	v_ashrrev_i32_e32 v173, 31, v172
	v_lshl_add_u64 v[170:171], s[16:17], 0, v[204:205]
	v_lshlrev_b64 v[206:207], 11, v[172:173]
	v_lshl_add_u64 v[128:129], v[170:171], 0, v[206:207]
	global_load_dwordx4 v[192:195], v[128:129], off
	global_load_dwordx4 v[198:201], v[128:129], off offset:256
	v_or_b32_e32 v182, 16, v172
	v_or_b32_e32 v178, 32, v172
	v_or_b32_e32 v174, 48, v172
	v_ashrrev_i32_e32 v183, 31, v182
	v_ashrrev_i32_e32 v179, 31, v178
	v_ashrrev_i32_e32 v175, 31, v174
	v_lshlrev_b64 v[184:185], 11, v[182:183]
	v_lshlrev_b64 v[180:181], 11, v[178:179]
	v_lshlrev_b64 v[176:177], 11, v[174:175]
	v_lshl_add_u64 v[128:129], v[170:171], 0, v[184:185]
	v_lshl_add_u64 v[130:131], v[170:171], 0, v[180:181]
	v_lshl_add_u64 v[208:209], v[170:171], 0, v[176:177]
	global_load_dwordx4 v[148:151], v[128:129], off
	global_load_dwordx4 v[144:147], v[128:129], off offset:256
	global_load_dwordx4 v[140:143], v[130:131], off
	global_load_dwordx4 v[136:139], v[130:131], off offset:256
	global_load_dwordx4 v[132:135], v[208:209], off
	s_nop 0
	global_load_dwordx4 v[128:131], v[208:209], off offset:256
	v_add_u32_e32 v248, 0x80, v172
	v_ashrrev_i32_e32 v249, 31, v248
	v_lshlrev_b64 v[248:249], 11, v[248:249]
	v_lshl_add_u64 v[248:249], v[170:171], 0, v[248:249]
	global_load_dwordx4 v[216:219], v[248:249], off
	global_load_dwordx4 v[220:223], v[248:249], off offset:256
	v_add_u32_e32 v250, 0x90, v172
	v_ashrrev_i32_e32 v251, 31, v250
	v_lshlrev_b64 v[250:251], 11, v[250:251]
	v_lshl_add_u64 v[250:251], v[170:171], 0, v[250:251]
	global_load_dwordx4 v[224:227], v[250:251], off
	global_load_dwordx4 v[228:231], v[250:251], off offset:256
	v_add_u32_e32 v252, 0xa0, v172
	v_ashrrev_i32_e32 v253, 31, v252
	v_lshlrev_b64 v[252:253], 11, v[252:253]
	v_lshl_add_u64 v[252:253], v[170:171], 0, v[252:253]
	global_load_dwordx4 v[232:235], v[252:253], off
	global_load_dwordx4 v[236:239], v[252:253], off offset:256
	v_add_u32_e32 v248, 0xb0, v172
	v_ashrrev_i32_e32 v249, 31, v248
	v_lshlrev_b64 v[248:249], 11, v[248:249]
	v_lshl_add_u64 v[248:249], v[170:171], 0, v[248:249]
	global_load_dwordx4 v[240:243], v[248:249], off
	global_load_dwordx4 v[244:247], v[248:249], off offset:256
	s_lshl_b32 s40, s10, 2
	s_ashr_i32 s41, s40, 31
	s_waitcnt vmcnt(8)
	v_lshlrev_b32_e32 v208, 16, v192
	v_and_b32_e32 v209, 0xffff0000, v192
	v_lshlrev_b32_e32 v192, 16, v193
	v_and_b32_e32 v193, 0xffff0000, v193
	v_lshlrev_b32_e32 v210, 16, v194
	v_and_b32_e32 v211, 0xffff0000, v194
	v_lshlrev_b32_e32 v194, 16, v195
	v_and_b32_e32 v195, 0xffff0000, v195
	v_lshlrev_b32_e32 v212, 16, v198
	v_and_b32_e32 v213, 0xffff0000, v198
	v_lshlrev_b32_e32 v198, 16, v199
	v_and_b32_e32 v199, 0xffff0000, v199
	v_lshlrev_b32_e32 v214, 16, v200
	v_and_b32_e32 v215, 0xffff0000, v200
	v_lshlrev_b32_e32 v200, 16, v201
	v_and_b32_e32 v201, 0xffff0000, v201
	v_pk_add_f32 v[126:127], v[126:127], v[192:193]
	v_pk_add_f32 v[124:125], v[124:125], v[208:209]
	v_pk_add_f32 v[122:123], v[122:123], v[194:195]
	v_pk_add_f32 v[120:121], v[120:121], v[210:211]
	v_pk_add_f32 v[118:119], v[118:119], v[198:199]
	v_pk_add_f32 v[116:117], v[116:117], v[212:213]
	v_pk_add_f32 v[192:193], v[114:115], v[200:201]
	v_pk_add_f32 v[194:195], v[112:113], v[214:215]
	v_mul_f32_e32 v198, v125, v125
	v_mul_f32_e32 v199, v127, v127
	v_mul_f32_e32 v200, v121, v121
	v_mul_f32_e32 v201, v123, v123
	v_cvt_pk_bf16_f32 v112, v124, v125
	v_cvt_pk_bf16_f32 v113, v126, v127
	v_cvt_pk_bf16_f32 v114, v120, v121
	v_cvt_pk_bf16_f32 v115, v122, v123
	v_mul_f32_e32 v121, v117, v117
	v_mul_f32_e32 v123, v119, v119
	v_mul_f32_e32 v125, v195, v195
	v_mul_f32_e32 v127, v193, v193
	v_fmac_f32_e32 v198, v124, v124
	v_fmac_f32_e32 v199, v126, v126
	v_fmac_f32_e32 v200, v120, v120
	v_fmac_f32_e32 v201, v122, v122
	v_fmac_f32_e32 v121, v116, v116
	v_fmac_f32_e32 v123, v118, v118
	v_fmac_f32_e32 v125, v194, v194
	v_fmac_f32_e32 v127, v192, v192
	v_add_f32_e32 v120, v198, v199
	v_add_f32_e32 v122, v200, v201
	v_add_f32_e32 v121, v121, v123
	v_add_f32_e32 v123, v125, v127
	v_add_f32_e32 v120, v120, v122
	v_add_f32_e32 v121, v121, v123
	v_add_f32_e32 v122, v120, v121
	ds_bpermute_b32 v123, v196, v122
	v_lshl_add_u64 v[120:121], s[16:17], 0, v[206:207]
	v_lshl_add_u64 v[120:121], v[120:121], 0, v[204:205]
	global_store_dwordx4 v[120:121], v[112:115], off
	s_waitcnt lgkmcnt(0)
	s_nop 0
	v_add_f32_e32 v112, v122, v123
	ds_bpermute_b32 v113, v197, v112
	v_cvt_pk_bf16_f32 v114, v116, v117
	v_cvt_pk_bf16_f32 v115, v118, v119
	v_cvt_pk_bf16_f32 v116, v194, v195
	v_cvt_pk_bf16_f32 v117, v192, v193
	global_store_dwordx4 v[120:121], v[114:117], off offset:256
	s_and_saveexec_b64 s[4:5], s[6:7]
	s_cbranch_execz .LBB0_971
	v_lshlrev_b64 v[114:115], 6, v[172:173]
	v_lshl_add_u64 v[114:115], s[24:25], 0, v[114:115]
	v_lshl_add_u64 v[114:115], s[40:41], 2, v[114:115]
	s_lshl_b32 s10, s49, 2
	v_lshl_add_u64 v[114:115], v[114:115], 0, s[10:11]
	s_waitcnt lgkmcnt(0)
	v_add_f32_e32 v112, v112, v113
	global_store_dword v[114:115], v112, off

.LBB0_977:
	s_or_b64 exec, exec, s[4:5]
	v_add_u32_e32 v100, 0x80, v172
	v_ashrrev_i32_e32 v101, 31, v100
	v_lshlrev_b64 v[110:111], 11, v[100:101]
	s_waitcnt lgkmcnt(0)
	v_lshl_add_u64 v[64:65], v[170:171], 0, v[110:111]
	v_add_u32_e32 v96, 0x90, v172
	v_add_u32_e32 v92, 0xa0, v172
	v_add_u32_e32 v88, 0xb0, v172
	v_ashrrev_i32_e32 v97, 31, v96
	v_ashrrev_i32_e32 v93, 31, v92
	v_ashrrev_i32_e32 v89, 31, v88
	v_lshlrev_b64 v[98:99], 11, v[96:97]
	v_lshlrev_b64 v[94:95], 11, v[92:93]
	v_lshlrev_b64 v[90:91], 11, v[88:89]
	v_lshl_add_u64 v[64:65], v[170:171], 0, v[98:99]
	v_lshl_add_u64 v[66:67], v[170:171], 0, v[94:95]
	v_lshl_add_u64 v[112:113], v[170:171], 0, v[90:91]
	s_waitcnt vmcnt(15)
	v_lshlrev_b32_e32 v112, 16, v216
	v_and_b32_e32 v113, 0xffff0000, v216
	v_lshlrev_b32_e32 v102, 16, v217
	v_and_b32_e32 v103, 0xffff0000, v217
	v_lshlrev_b32_e32 v114, 16, v218
	v_and_b32_e32 v115, 0xffff0000, v218
	v_lshlrev_b32_e32 v104, 16, v219
	v_and_b32_e32 v105, 0xffff0000, v219
	s_waitcnt vmcnt(14)
	v_lshlrev_b32_e32 v116, 16, v220
	v_and_b32_e32 v117, 0xffff0000, v220
	v_lshlrev_b32_e32 v106, 16, v221
	v_and_b32_e32 v107, 0xffff0000, v221
	v_lshlrev_b32_e32 v118, 16, v222
	v_and_b32_e32 v119, 0xffff0000, v222
	v_lshlrev_b32_e32 v108, 16, v223
	v_and_b32_e32 v109, 0xffff0000, v223
	v_pk_add_f32 v[62:63], v[62:63], v[102:103]
	v_pk_add_f32 v[60:61], v[60:61], v[112:113]
	v_pk_add_f32 v[58:59], v[58:59], v[104:105]
	v_pk_add_f32 v[56:57], v[56:57], v[114:115]
	v_pk_add_f32 v[54:55], v[54:55], v[106:107]
	v_pk_add_f32 v[52:53], v[52:53], v[116:117]
	v_pk_add_f32 v[102:103], v[50:51], v[108:109]
	v_pk_add_f32 v[104:105], v[48:49], v[118:119]
	v_mul_f32_e32 v106, v61, v61
	v_mul_f32_e32 v107, v63, v63
	v_mul_f32_e32 v108, v57, v57
	v_mul_f32_e32 v109, v59, v59
	v_cvt_pk_bf16_f32 v48, v60, v61
	v_cvt_pk_bf16_f32 v49, v62, v63
	v_cvt_pk_bf16_f32 v50, v56, v57
	v_cvt_pk_bf16_f32 v51, v58, v59
	v_mul_f32_e32 v57, v53, v53
	v_mul_f32_e32 v59, v55, v55
	v_mul_f32_e32 v61, v105, v105
	v_mul_f32_e32 v63, v103, v103
	v_fmac_f32_e32 v106, v60, v60
	v_fmac_f32_e32 v107, v62, v62
	v_fmac_f32_e32 v108, v56, v56
	v_fmac_f32_e32 v109, v58, v58
	v_fmac_f32_e32 v57, v52, v52
	v_fmac_f32_e32 v59, v54, v54
	v_fmac_f32_e32 v61, v104, v104
	v_fmac_f32_e32 v63, v102, v102
	v_add_f32_e32 v56, v106, v107
	v_add_f32_e32 v58, v108, v109
	v_add_f32_e32 v57, v57, v59
	v_add_f32_e32 v59, v61, v63
	v_add_f32_e32 v56, v56, v58
	v_add_f32_e32 v57, v57, v59
	v_add_f32_e32 v58, v56, v57
	ds_bpermute_b32 v59, v196, v58
	v_lshl_add_u64 v[56:57], s[16:17], 0, v[110:111]
	v_lshl_add_u64 v[56:57], v[168:169], 1, v[56:57]
	global_store_dwordx4 v[56:57], v[48:51], off
	s_waitcnt lgkmcnt(0)
	s_nop 0
	v_add_f32_e32 v48, v58, v59
	ds_bpermute_b32 v49, v197, v48
	v_cvt_pk_bf16_f32 v50, v52, v53
	v_cvt_pk_bf16_f32 v51, v54, v55
	v_cvt_pk_bf16_f32 v52, v104, v105
	v_cvt_pk_bf16_f32 v53, v102, v103
	global_store_dwordx4 v[56:57], v[50:53], off offset:256
	s_and_saveexec_b64 s[4:5], s[6:7]
	s_cbranch_execz .LBB0_979
	v_lshlrev_b64 v[50:51], 6, v[100:101]
	v_lshl_add_u64 v[50:51], s[24:25], 0, v[50:51]
	v_lshl_add_u64 v[50:51], s[40:41], 2, v[50:51]
	s_lshl_b32 s10, s49, 2
	v_lshl_add_u64 v[50:51], v[50:51], 0, s[10:11]
	s_waitcnt lgkmcnt(0)
	v_add_f32_e32 v48, v48, v49
	global_store_dword v[50:51], v48, off
.LBB0_979:
	s_or_b64 exec, exec, s[4:5]
	s_waitcnt vmcnt(15)
	v_lshlrev_b32_e32 v48, 16, v224
	s_waitcnt lgkmcnt(0)
	v_and_b32_e32 v49, 0xffff0000, v224
	v_lshlrev_b32_e32 v50, 16, v225
	v_and_b32_e32 v51, 0xffff0000, v225
	v_lshlrev_b32_e32 v52, 16, v226
	v_and_b32_e32 v53, 0xffff0000, v226
	v_lshlrev_b32_e32 v54, 16, v227
	v_and_b32_e32 v55, 0xffff0000, v227
	v_pk_add_f32 v[46:47], v[46:47], v[50:51]
	v_pk_add_f32 v[44:45], v[44:45], v[48:49]
	v_pk_add_f32 v[48:49], v[42:43], v[54:55]
	v_pk_add_f32 v[42:43], v[40:41], v[52:53]
	v_mul_f32_e32 v40, v45, v45
	v_mul_f32_e32 v41, v47, v47
	v_fmac_f32_e32 v40, v44, v44
	v_fmac_f32_e32 v41, v46, v46
	v_add_f32_e32 v40, v40, v41
	v_mul_f32_e32 v41, v43, v43
	v_mul_f32_e32 v50, v49, v49
	v_fmac_f32_e32 v41, v42, v42
	v_fmac_f32_e32 v50, v48, v48
	v_add_f32_e32 v41, v41, v50
	v_add_f32_e32 v52, v40, v41
	v_cvt_pk_bf16_f32 v40, v44, v45
	v_cvt_pk_bf16_f32 v41, v46, v47
	s_waitcnt vmcnt(14)
	v_lshlrev_b32_e32 v44, 16, v228
	v_and_b32_e32 v45, 0xffff0000, v228
	v_lshlrev_b32_e32 v46, 16, v229
	v_and_b32_e32 v47, 0xffff0000, v229
	v_cvt_pk_bf16_f32 v42, v42, v43
	v_cvt_pk_bf16_f32 v43, v48, v49
	v_lshlrev_b32_e32 v48, 16, v230
	v_and_b32_e32 v49, 0xffff0000, v230
	v_pk_add_f32 v[38:39], v[38:39], v[46:47]
	v_pk_add_f32 v[36:37], v[36:37], v[44:45]
	v_lshlrev_b32_e32 v50, 16, v231
	v_and_b32_e32 v51, 0xffff0000, v231
	v_pk_add_f32 v[46:47], v[32:33], v[48:49]
	v_mul_f32_e32 v32, v37, v37
	v_mul_f32_e32 v33, v39, v39
	v_pk_add_f32 v[44:45], v[34:35], v[50:51]
	v_fmac_f32_e32 v32, v36, v36
	v_fmac_f32_e32 v33, v38, v38
	v_add_f32_e32 v32, v32, v33
	v_mul_f32_e32 v33, v47, v47
	v_mul_f32_e32 v34, v45, v45
	v_fmac_f32_e32 v33, v46, v46
	v_fmac_f32_e32 v34, v44, v44
	v_add_f32_e32 v33, v33, v34
	v_add_f32_e32 v32, v32, v33
	v_add_f32_e32 v35, v52, v32
	ds_bpermute_b32 v50, v196, v35
	v_lshl_add_u64 v[32:33], s[16:17], 0, v[98:99]
	v_lshl_add_u64 v[48:49], v[168:169], 1, v[32:33]
	global_store_dwordx4 v[48:49], v[40:43], off
	v_cvt_pk_bf16_f32 v34, v36, v37
	s_waitcnt lgkmcnt(0)
	v_add_f32_e32 v32, v35, v50
	ds_bpermute_b32 v33, v197, v32
	v_cvt_pk_bf16_f32 v35, v38, v39
	v_cvt_pk_bf16_f32 v36, v46, v47
	v_cvt_pk_bf16_f32 v37, v44, v45
	global_store_dwordx4 v[48:49], v[34:37], off offset:256
	s_and_saveexec_b64 s[4:5], s[6:7]
	s_cbranch_execz .LBB0_981
	v_lshlrev_b64 v[34:35], 6, v[96:97]
	v_lshl_add_u64 v[34:35], s[24:25], 0, v[34:35]
	v_lshl_add_u64 v[34:35], s[40:41], 2, v[34:35]
	s_lshl_b32 s10, s49, 2
	v_lshl_add_u64 v[34:35], v[34:35], 0, s[10:11]
	s_waitcnt lgkmcnt(0)
	v_add_f32_e32 v32, v32, v33
	global_store_dword v[34:35], v32, off
.LBB0_981:
	s_or_b64 exec, exec, s[4:5]
	s_waitcnt vmcnt(15)
	v_lshlrev_b32_e32 v32, 16, v232
	s_waitcnt lgkmcnt(0)
	v_and_b32_e32 v33, 0xffff0000, v232
	v_lshlrev_b32_e32 v34, 16, v233
	v_and_b32_e32 v35, 0xffff0000, v233
	v_lshlrev_b32_e32 v36, 16, v234
	v_and_b32_e32 v37, 0xffff0000, v234
	v_lshlrev_b32_e32 v38, 16, v235
	v_and_b32_e32 v39, 0xffff0000, v235
	v_pk_add_f32 v[30:31], v[30:31], v[34:35]
	v_pk_add_f32 v[28:29], v[28:29], v[32:33]
	v_pk_add_f32 v[32:33], v[26:27], v[38:39]
	v_pk_add_f32 v[26:27], v[24:25], v[36:37]
	v_mul_f32_e32 v24, v29, v29
	v_mul_f32_e32 v25, v31, v31
	v_fmac_f32_e32 v24, v28, v28
	v_fmac_f32_e32 v25, v30, v30
	v_add_f32_e32 v24, v24, v25
	v_mul_f32_e32 v25, v27, v27
	v_mul_f32_e32 v34, v33, v33
	v_fmac_f32_e32 v25, v26, v26
	v_fmac_f32_e32 v34, v32, v32
	v_add_f32_e32 v25, v25, v34
	v_add_f32_e32 v36, v24, v25
	v_cvt_pk_bf16_f32 v24, v28, v29
	v_cvt_pk_bf16_f32 v25, v30, v31
	s_waitcnt vmcnt(14)
	v_lshlrev_b32_e32 v28, 16, v236
	v_and_b32_e32 v29, 0xffff0000, v236
	v_lshlrev_b32_e32 v30, 16, v237
	v_and_b32_e32 v31, 0xffff0000, v237
	v_cvt_pk_bf16_f32 v26, v26, v27
	v_cvt_pk_bf16_f32 v27, v32, v33
	v_lshlrev_b32_e32 v32, 16, v238
	v_and_b32_e32 v33, 0xffff0000, v238
	v_pk_add_f32 v[22:23], v[22:23], v[30:31]
	v_pk_add_f32 v[20:21], v[20:21], v[28:29]
	v_lshlrev_b32_e32 v34, 16, v239
	v_and_b32_e32 v35, 0xffff0000, v239
	v_pk_add_f32 v[30:31], v[16:17], v[32:33]
	v_mul_f32_e32 v16, v21, v21
	v_mul_f32_e32 v17, v23, v23
	v_pk_add_f32 v[28:29], v[18:19], v[34:35]
	v_fmac_f32_e32 v16, v20, v20
	v_fmac_f32_e32 v17, v22, v22
	v_add_f32_e32 v16, v16, v17
	v_mul_f32_e32 v17, v31, v31
	v_mul_f32_e32 v18, v29, v29
	v_fmac_f32_e32 v17, v30, v30
	v_fmac_f32_e32 v18, v28, v28
	v_add_f32_e32 v17, v17, v18
	v_add_f32_e32 v16, v16, v17
	v_add_f32_e32 v19, v36, v16
	ds_bpermute_b32 v34, v196, v19
	v_lshl_add_u64 v[16:17], s[16:17], 0, v[94:95]
	v_lshl_add_u64 v[32:33], v[168:169], 1, v[16:17]
	global_store_dwordx4 v[32:33], v[24:27], off
	v_cvt_pk_bf16_f32 v18, v20, v21
	s_waitcnt lgkmcnt(0)
	v_add_f32_e32 v16, v19, v34
	ds_bpermute_b32 v17, v197, v16
	v_cvt_pk_bf16_f32 v19, v22, v23
	v_cvt_pk_bf16_f32 v20, v30, v31
	v_cvt_pk_bf16_f32 v21, v28, v29
	global_store_dwordx4 v[32:33], v[18:21], off offset:256
	s_and_saveexec_b64 s[4:5], s[6:7]
	s_cbranch_execz .LBB0_983
	v_lshlrev_b64 v[18:19], 6, v[92:93]
	v_lshl_add_u64 v[18:19], s[24:25], 0, v[18:19]
	v_lshl_add_u64 v[18:19], s[40:41], 2, v[18:19]
	s_lshl_b32 s10, s49, 2
	v_lshl_add_u64 v[18:19], v[18:19], 0, s[10:11]
	s_waitcnt lgkmcnt(0)
	v_add_f32_e32 v16, v16, v17
	global_store_dword v[18:19], v16, off
.LBB0_983:
	s_or_b64 exec, exec, s[4:5]
	s_waitcnt vmcnt(15)
	v_lshlrev_b32_e32 v16, 16, v240
	s_waitcnt lgkmcnt(0)
	v_and_b32_e32 v17, 0xffff0000, v240
	v_lshlrev_b32_e32 v18, 16, v241
	v_and_b32_e32 v19, 0xffff0000, v241
	v_lshlrev_b32_e32 v20, 16, v242
	v_and_b32_e32 v21, 0xffff0000, v242
	v_lshlrev_b32_e32 v22, 16, v243
	v_and_b32_e32 v23, 0xffff0000, v243
	v_pk_add_f32 v[14:15], v[14:15], v[18:19]
	v_pk_add_f32 v[12:13], v[12:13], v[16:17]
	v_pk_add_f32 v[16:17], v[10:11], v[22:23]
	v_pk_add_f32 v[10:11], v[8:9], v[20:21]
	v_mul_f32_e32 v8, v13, v13
	v_mul_f32_e32 v9, v15, v15
	v_fmac_f32_e32 v8, v12, v12
	v_fmac_f32_e32 v9, v14, v14
	v_add_f32_e32 v8, v8, v9
	v_mul_f32_e32 v9, v11, v11
	v_mul_f32_e32 v18, v17, v17
	v_fmac_f32_e32 v9, v10, v10
	v_fmac_f32_e32 v18, v16, v16
	v_add_f32_e32 v9, v9, v18
	v_add_f32_e32 v20, v8, v9
	v_cvt_pk_bf16_f32 v8, v12, v13
	v_cvt_pk_bf16_f32 v9, v14, v15
	s_waitcnt vmcnt(14)
	v_lshlrev_b32_e32 v12, 16, v244
	v_and_b32_e32 v13, 0xffff0000, v244
	v_lshlrev_b32_e32 v14, 16, v245
	v_and_b32_e32 v15, 0xffff0000, v245
	v_cvt_pk_bf16_f32 v10, v10, v11
	v_cvt_pk_bf16_f32 v11, v16, v17
	v_lshlrev_b32_e32 v16, 16, v246
	v_and_b32_e32 v17, 0xffff0000, v246
	v_pk_add_f32 v[6:7], v[6:7], v[14:15]
	v_pk_add_f32 v[4:5], v[4:5], v[12:13]
	v_lshlrev_b32_e32 v18, 16, v247
	v_and_b32_e32 v19, 0xffff0000, v247
	v_pk_add_f32 v[14:15], v[0:1], v[16:17]
	v_mul_f32_e32 v0, v5, v5
	v_mul_f32_e32 v1, v7, v7
	v_pk_add_f32 v[12:13], v[2:3], v[18:19]
	v_fmac_f32_e32 v0, v4, v4
	v_fmac_f32_e32 v1, v6, v6
	v_add_f32_e32 v0, v0, v1
	v_mul_f32_e32 v1, v15, v15
	v_mul_f32_e32 v2, v13, v13
	v_fmac_f32_e32 v1, v14, v14
	v_fmac_f32_e32 v2, v12, v12
	v_add_f32_e32 v1, v1, v2
	v_add_f32_e32 v0, v0, v1
	v_add_f32_e32 v3, v20, v0
	ds_bpermute_b32 v18, v196, v3
	v_lshl_add_u64 v[0:1], s[16:17], 0, v[90:91]
	v_lshl_add_u64 v[16:17], v[168:169], 1, v[0:1]
	global_store_dwordx4 v[16:17], v[8:11], off
	v_cvt_pk_bf16_f32 v2, v4, v5
	s_waitcnt lgkmcnt(0)
	v_add_f32_e32 v0, v3, v18
	ds_bpermute_b32 v1, v197, v0
	v_cvt_pk_bf16_f32 v3, v6, v7
	v_cvt_pk_bf16_f32 v4, v14, v15
	v_cvt_pk_bf16_f32 v5, v12, v13
	global_store_dwordx4 v[16:17], v[2:5], off offset:256
	s_and_saveexec_b64 s[4:5], s[6:7]
	s_cbranch_execz .LBB0_985
	v_lshlrev_b64 v[2:3], 6, v[88:89]
	v_lshl_add_u64 v[2:3], s[24:25], 0, v[2:3]
	v_lshl_add_u64 v[2:3], s[40:41], 2, v[2:3]
	s_lshl_b32 s10, s49, 2
	v_lshl_add_u64 v[2:3], v[2:3], 0, s[10:11]
	s_waitcnt lgkmcnt(0)
	v_add_f32_e32 v0, v0, v1
	global_store_dword v[2:3], v0, off

.LBB0_1127:
	v_lshl_or_b32 v168, s10, 8, v188
	v_lshl_add_u32 v172, s53, 8, v186
	v_ashrrev_i32_e32 v169, 31, v168
	v_lshlrev_b64 v[204:205], 1, v[168:169]
	v_ashrrev_i32_e32 v173, 31, v172
	v_lshl_add_u64 v[170:171], s[16:17], 0, v[204:205]
	v_lshlrev_b64 v[206:207], 11, v[172:173]
	v_lshl_add_u64 v[128:129], v[170:171], 0, v[206:207]
	global_load_dwordx4 v[192:195], v[128:129], off
	global_load_dwordx4 v[198:201], v[128:129], off offset:256
	v_or_b32_e32 v182, 16, v172
	v_or_b32_e32 v178, 32, v172
	v_or_b32_e32 v174, 48, v172
	v_ashrrev_i32_e32 v183, 31, v182
	v_ashrrev_i32_e32 v179, 31, v178
	v_ashrrev_i32_e32 v175, 31, v174
	v_lshlrev_b64 v[184:185], 11, v[182:183]
	v_lshlrev_b64 v[180:181], 11, v[178:179]
	v_lshlrev_b64 v[176:177], 11, v[174:175]
	v_lshl_add_u64 v[128:129], v[170:171], 0, v[184:185]
	v_lshl_add_u64 v[130:131], v[170:171], 0, v[180:181]
	v_lshl_add_u64 v[208:209], v[170:171], 0, v[176:177]
	global_load_dwordx4 v[148:151], v[128:129], off
	global_load_dwordx4 v[144:147], v[128:129], off offset:256
	global_load_dwordx4 v[140:143], v[130:131], off
	global_load_dwordx4 v[136:139], v[130:131], off offset:256
	global_load_dwordx4 v[132:135], v[208:209], off
	s_nop 0
	global_load_dwordx4 v[128:131], v[208:209], off offset:256
	v_add_u32_e32 v248, 0x80, v172
	v_ashrrev_i32_e32 v249, 31, v248
	v_lshlrev_b64 v[248:249], 11, v[248:249]
	v_lshl_add_u64 v[248:249], v[170:171], 0, v[248:249]
	global_load_dwordx4 v[216:219], v[248:249], off
	global_load_dwordx4 v[220:223], v[248:249], off offset:256
	v_add_u32_e32 v250, 0x90, v172
	v_ashrrev_i32_e32 v251, 31, v250
	v_lshlrev_b64 v[250:251], 11, v[250:251]
	v_lshl_add_u64 v[250:251], v[170:171], 0, v[250:251]
	global_load_dwordx4 v[224:227], v[250:251], off
	global_load_dwordx4 v[228:231], v[250:251], off offset:256
	v_add_u32_e32 v252, 0xa0, v172
	v_ashrrev_i32_e32 v253, 31, v252
	v_lshlrev_b64 v[252:253], 11, v[252:253]
	v_lshl_add_u64 v[252:253], v[170:171], 0, v[252:253]
	global_load_dwordx4 v[232:235], v[252:253], off
	global_load_dwordx4 v[236:239], v[252:253], off offset:256
	v_add_u32_e32 v248, 0xb0, v172
	v_ashrrev_i32_e32 v249, 31, v248
	v_lshlrev_b64 v[248:249], 11, v[248:249]
	v_lshl_add_u64 v[248:249], v[170:171], 0, v[248:249]
	global_load_dwordx4 v[240:243], v[248:249], off
	global_load_dwordx4 v[244:247], v[248:249], off offset:256
	s_lshl_b32 s30, s10, 2
	s_ashr_i32 s31, s30, 31
	s_waitcnt vmcnt(8)
	v_lshlrev_b32_e32 v208, 16, v192
	v_and_b32_e32 v209, 0xffff0000, v192
	v_lshlrev_b32_e32 v192, 16, v193
	v_and_b32_e32 v193, 0xffff0000, v193
	v_lshlrev_b32_e32 v210, 16, v194
	v_and_b32_e32 v211, 0xffff0000, v194
	v_lshlrev_b32_e32 v194, 16, v195
	v_and_b32_e32 v195, 0xffff0000, v195
	v_lshlrev_b32_e32 v212, 16, v198
	v_and_b32_e32 v213, 0xffff0000, v198
	v_lshlrev_b32_e32 v198, 16, v199
	v_and_b32_e32 v199, 0xffff0000, v199
	v_lshlrev_b32_e32 v214, 16, v200
	v_and_b32_e32 v215, 0xffff0000, v200
	v_lshlrev_b32_e32 v200, 16, v201
	v_and_b32_e32 v201, 0xffff0000, v201
	v_pk_add_f32 v[126:127], v[126:127], v[192:193]
	v_pk_add_f32 v[124:125], v[124:125], v[208:209]
	v_pk_add_f32 v[122:123], v[122:123], v[194:195]
	v_pk_add_f32 v[120:121], v[120:121], v[210:211]
	v_pk_add_f32 v[118:119], v[118:119], v[198:199]
	v_pk_add_f32 v[116:117], v[116:117], v[212:213]
	v_pk_add_f32 v[192:193], v[114:115], v[200:201]
	v_pk_add_f32 v[194:195], v[112:113], v[214:215]
	v_mul_f32_e32 v198, v125, v125
	v_mul_f32_e32 v199, v127, v127
	v_mul_f32_e32 v200, v121, v121
	v_mul_f32_e32 v201, v123, v123
	v_cvt_pk_bf16_f32 v112, v124, v125
	v_cvt_pk_bf16_f32 v113, v126, v127
	v_cvt_pk_bf16_f32 v114, v120, v121
	v_cvt_pk_bf16_f32 v115, v122, v123
	v_mul_f32_e32 v121, v117, v117
	v_mul_f32_e32 v123, v119, v119
	v_mul_f32_e32 v125, v195, v195
	v_mul_f32_e32 v127, v193, v193
	v_fmac_f32_e32 v198, v124, v124
	v_fmac_f32_e32 v199, v126, v126
	v_fmac_f32_e32 v200, v120, v120
	v_fmac_f32_e32 v201, v122, v122
	v_fmac_f32_e32 v121, v116, v116
	v_fmac_f32_e32 v123, v118, v118
	v_fmac_f32_e32 v125, v194, v194
	v_fmac_f32_e32 v127, v192, v192
	v_add_f32_e32 v120, v198, v199
	v_add_f32_e32 v122, v200, v201
	v_add_f32_e32 v121, v121, v123
	v_add_f32_e32 v123, v125, v127
	v_add_f32_e32 v120, v120, v122
	v_add_f32_e32 v121, v121, v123
	v_add_f32_e32 v122, v120, v121
	ds_bpermute_b32 v123, v196, v122
	v_lshl_add_u64 v[120:121], s[16:17], 0, v[206:207]
	v_lshl_add_u64 v[120:121], v[120:121], 0, v[204:205]
	global_store_dwordx4 v[120:121], v[112:115], off
	s_waitcnt lgkmcnt(0)
	s_nop 0
	v_add_f32_e32 v112, v122, v123
	ds_bpermute_b32 v113, v197, v112
	v_cvt_pk_bf16_f32 v114, v116, v117
	v_cvt_pk_bf16_f32 v115, v118, v119
	v_cvt_pk_bf16_f32 v116, v194, v195
	v_cvt_pk_bf16_f32 v117, v192, v193
	global_store_dwordx4 v[120:121], v[114:117], off offset:256
	s_and_saveexec_b64 s[34:35], s[4:5]
	s_cbranch_execz .LBB0_1129
	v_lshlrev_b64 v[114:115], 6, v[172:173]
	v_lshl_add_u64 v[114:115], s[22:23], 0, v[114:115]
	v_lshl_add_u64 v[114:115], s[30:31], 2, v[114:115]
	s_lshl_b32 s10, s45, 2
	v_lshl_add_u64 v[114:115], v[114:115], 0, s[10:11]
	s_waitcnt lgkmcnt(0)
	v_add_f32_e32 v112, v112, v113
	global_store_dword v[114:115], v112, off

.LBB0_1135:
	s_or_b64 exec, exec, s[34:35]
	v_add_u32_e32 v100, 0x80, v172
	v_ashrrev_i32_e32 v101, 31, v100
	v_lshlrev_b64 v[110:111], 11, v[100:101]
	s_waitcnt lgkmcnt(0)
	v_lshl_add_u64 v[64:65], v[170:171], 0, v[110:111]
	v_add_u32_e32 v96, 0x90, v172
	v_add_u32_e32 v92, 0xa0, v172
	v_add_u32_e32 v88, 0xb0, v172
	v_ashrrev_i32_e32 v97, 31, v96
	v_ashrrev_i32_e32 v93, 31, v92
	v_ashrrev_i32_e32 v89, 31, v88
	v_lshlrev_b64 v[98:99], 11, v[96:97]
	v_lshlrev_b64 v[94:95], 11, v[92:93]
	v_lshlrev_b64 v[90:91], 11, v[88:89]
	v_lshl_add_u64 v[64:65], v[170:171], 0, v[98:99]
	v_lshl_add_u64 v[66:67], v[170:171], 0, v[94:95]
	v_lshl_add_u64 v[112:113], v[170:171], 0, v[90:91]
	s_waitcnt vmcnt(15)
	v_lshlrev_b32_e32 v112, 16, v216
	v_and_b32_e32 v113, 0xffff0000, v216
	v_lshlrev_b32_e32 v102, 16, v217
	v_and_b32_e32 v103, 0xffff0000, v217
	v_lshlrev_b32_e32 v114, 16, v218
	v_and_b32_e32 v115, 0xffff0000, v218
	v_lshlrev_b32_e32 v104, 16, v219
	v_and_b32_e32 v105, 0xffff0000, v219
	s_waitcnt vmcnt(14)
	v_lshlrev_b32_e32 v116, 16, v220
	v_and_b32_e32 v117, 0xffff0000, v220
	v_lshlrev_b32_e32 v106, 16, v221
	v_and_b32_e32 v107, 0xffff0000, v221
	v_lshlrev_b32_e32 v118, 16, v222
	v_and_b32_e32 v119, 0xffff0000, v222
	v_lshlrev_b32_e32 v108, 16, v223
	v_and_b32_e32 v109, 0xffff0000, v223
	v_pk_add_f32 v[62:63], v[62:63], v[102:103]
	v_pk_add_f32 v[60:61], v[60:61], v[112:113]
	v_pk_add_f32 v[58:59], v[58:59], v[104:105]
	v_pk_add_f32 v[56:57], v[56:57], v[114:115]
	v_pk_add_f32 v[54:55], v[54:55], v[106:107]
	v_pk_add_f32 v[52:53], v[52:53], v[116:117]
	v_pk_add_f32 v[102:103], v[50:51], v[108:109]
	v_pk_add_f32 v[104:105], v[48:49], v[118:119]
	v_mul_f32_e32 v106, v61, v61
	v_mul_f32_e32 v107, v63, v63
	v_mul_f32_e32 v108, v57, v57
	v_mul_f32_e32 v109, v59, v59
	v_cvt_pk_bf16_f32 v48, v60, v61
	v_cvt_pk_bf16_f32 v49, v62, v63
	v_cvt_pk_bf16_f32 v50, v56, v57
	v_cvt_pk_bf16_f32 v51, v58, v59
	v_mul_f32_e32 v57, v53, v53
	v_mul_f32_e32 v59, v55, v55
	v_mul_f32_e32 v61, v105, v105
	v_mul_f32_e32 v63, v103, v103
	v_fmac_f32_e32 v106, v60, v60
	v_fmac_f32_e32 v107, v62, v62
	v_fmac_f32_e32 v108, v56, v56
	v_fmac_f32_e32 v109, v58, v58
	v_fmac_f32_e32 v57, v52, v52
	v_fmac_f32_e32 v59, v54, v54
	v_fmac_f32_e32 v61, v104, v104
	v_fmac_f32_e32 v63, v102, v102
	v_add_f32_e32 v56, v106, v107
	v_add_f32_e32 v58, v108, v109
	v_add_f32_e32 v57, v57, v59
	v_add_f32_e32 v59, v61, v63
	v_add_f32_e32 v56, v56, v58
	v_add_f32_e32 v57, v57, v59
	v_add_f32_e32 v58, v56, v57
	ds_bpermute_b32 v59, v196, v58
	v_lshl_add_u64 v[56:57], s[16:17], 0, v[110:111]
	v_lshl_add_u64 v[56:57], v[168:169], 1, v[56:57]
	global_store_dwordx4 v[56:57], v[48:51], off
	s_waitcnt lgkmcnt(0)
	s_nop 0
	v_add_f32_e32 v48, v58, v59
	ds_bpermute_b32 v49, v197, v48
	v_cvt_pk_bf16_f32 v50, v52, v53
	v_cvt_pk_bf16_f32 v51, v54, v55
	v_cvt_pk_bf16_f32 v52, v104, v105
	v_cvt_pk_bf16_f32 v53, v102, v103
	global_store_dwordx4 v[56:57], v[50:53], off offset:256
	s_and_saveexec_b64 s[34:35], s[4:5]
	s_cbranch_execz .LBB0_1137
	v_lshlrev_b64 v[50:51], 6, v[100:101]
	v_lshl_add_u64 v[50:51], s[22:23], 0, v[50:51]
	v_lshl_add_u64 v[50:51], s[30:31], 2, v[50:51]
	s_lshl_b32 s10, s45, 2
	v_lshl_add_u64 v[50:51], v[50:51], 0, s[10:11]
	s_waitcnt lgkmcnt(0)
	v_add_f32_e32 v48, v48, v49
	global_store_dword v[50:51], v48, off
.LBB0_1137:
	s_or_b64 exec, exec, s[34:35]
	s_waitcnt vmcnt(15)
	v_lshlrev_b32_e32 v48, 16, v224
	s_waitcnt lgkmcnt(0)
	v_and_b32_e32 v49, 0xffff0000, v224
	v_lshlrev_b32_e32 v50, 16, v225
	v_and_b32_e32 v51, 0xffff0000, v225
	v_lshlrev_b32_e32 v52, 16, v226
	v_and_b32_e32 v53, 0xffff0000, v226
	v_lshlrev_b32_e32 v54, 16, v227
	v_and_b32_e32 v55, 0xffff0000, v227
	v_pk_add_f32 v[46:47], v[46:47], v[50:51]
	v_pk_add_f32 v[44:45], v[44:45], v[48:49]
	v_pk_add_f32 v[48:49], v[42:43], v[54:55]
	v_pk_add_f32 v[42:43], v[40:41], v[52:53]
	v_mul_f32_e32 v40, v45, v45
	v_mul_f32_e32 v41, v47, v47
	v_fmac_f32_e32 v40, v44, v44
	v_fmac_f32_e32 v41, v46, v46
	v_add_f32_e32 v40, v40, v41
	v_mul_f32_e32 v41, v43, v43
	v_mul_f32_e32 v50, v49, v49
	v_fmac_f32_e32 v41, v42, v42
	v_fmac_f32_e32 v50, v48, v48
	v_add_f32_e32 v41, v41, v50
	v_add_f32_e32 v52, v40, v41
	v_cvt_pk_bf16_f32 v40, v44, v45
	v_cvt_pk_bf16_f32 v41, v46, v47
	s_waitcnt vmcnt(14)
	v_lshlrev_b32_e32 v44, 16, v228
	v_and_b32_e32 v45, 0xffff0000, v228
	v_lshlrev_b32_e32 v46, 16, v229
	v_and_b32_e32 v47, 0xffff0000, v229
	v_cvt_pk_bf16_f32 v42, v42, v43
	v_cvt_pk_bf16_f32 v43, v48, v49
	v_lshlrev_b32_e32 v48, 16, v230
	v_and_b32_e32 v49, 0xffff0000, v230
	v_pk_add_f32 v[38:39], v[38:39], v[46:47]
	v_pk_add_f32 v[36:37], v[36:37], v[44:45]
	v_lshlrev_b32_e32 v50, 16, v231
	v_and_b32_e32 v51, 0xffff0000, v231
	v_pk_add_f32 v[46:47], v[32:33], v[48:49]
	v_mul_f32_e32 v32, v37, v37
	v_mul_f32_e32 v33, v39, v39
	v_pk_add_f32 v[44:45], v[34:35], v[50:51]
	v_fmac_f32_e32 v32, v36, v36
	v_fmac_f32_e32 v33, v38, v38
	v_add_f32_e32 v32, v32, v33
	v_mul_f32_e32 v33, v47, v47
	v_mul_f32_e32 v34, v45, v45
	v_fmac_f32_e32 v33, v46, v46
	v_fmac_f32_e32 v34, v44, v44
	v_add_f32_e32 v33, v33, v34
	v_add_f32_e32 v32, v32, v33
	v_add_f32_e32 v35, v52, v32
	ds_bpermute_b32 v50, v196, v35
	v_lshl_add_u64 v[32:33], s[16:17], 0, v[98:99]
	v_lshl_add_u64 v[48:49], v[168:169], 1, v[32:33]
	global_store_dwordx4 v[48:49], v[40:43], off
	v_cvt_pk_bf16_f32 v34, v36, v37
	s_waitcnt lgkmcnt(0)
	v_add_f32_e32 v32, v35, v50
	ds_bpermute_b32 v33, v197, v32
	v_cvt_pk_bf16_f32 v35, v38, v39
	v_cvt_pk_bf16_f32 v36, v46, v47
	v_cvt_pk_bf16_f32 v37, v44, v45
	global_store_dwordx4 v[48:49], v[34:37], off offset:256
	s_and_saveexec_b64 s[34:35], s[4:5]
	s_cbranch_execz .LBB0_1139
	v_lshlrev_b64 v[34:35], 6, v[96:97]
	v_lshl_add_u64 v[34:35], s[22:23], 0, v[34:35]
	v_lshl_add_u64 v[34:35], s[30:31], 2, v[34:35]
	s_lshl_b32 s10, s45, 2
	v_lshl_add_u64 v[34:35], v[34:35], 0, s[10:11]
	s_waitcnt lgkmcnt(0)
	v_add_f32_e32 v32, v32, v33
	global_store_dword v[34:35], v32, off
.LBB0_1139:
	s_or_b64 exec, exec, s[34:35]
	s_waitcnt vmcnt(15)
	v_lshlrev_b32_e32 v32, 16, v232
	s_waitcnt lgkmcnt(0)
	v_and_b32_e32 v33, 0xffff0000, v232
	v_lshlrev_b32_e32 v34, 16, v233
	v_and_b32_e32 v35, 0xffff0000, v233
	v_lshlrev_b32_e32 v36, 16, v234
	v_and_b32_e32 v37, 0xffff0000, v234
	v_lshlrev_b32_e32 v38, 16, v235
	v_and_b32_e32 v39, 0xffff0000, v235
	v_pk_add_f32 v[30:31], v[30:31], v[34:35]
	v_pk_add_f32 v[28:29], v[28:29], v[32:33]
	v_pk_add_f32 v[32:33], v[26:27], v[38:39]
	v_pk_add_f32 v[26:27], v[24:25], v[36:37]
	v_mul_f32_e32 v24, v29, v29
	v_mul_f32_e32 v25, v31, v31
	v_fmac_f32_e32 v24, v28, v28
	v_fmac_f32_e32 v25, v30, v30
	v_add_f32_e32 v24, v24, v25
	v_mul_f32_e32 v25, v27, v27
	v_mul_f32_e32 v34, v33, v33
	v_fmac_f32_e32 v25, v26, v26
	v_fmac_f32_e32 v34, v32, v32
	v_add_f32_e32 v25, v25, v34
	v_add_f32_e32 v36, v24, v25
	v_cvt_pk_bf16_f32 v24, v28, v29
	v_cvt_pk_bf16_f32 v25, v30, v31
	s_waitcnt vmcnt(14)
	v_lshlrev_b32_e32 v28, 16, v236
	v_and_b32_e32 v29, 0xffff0000, v236
	v_lshlrev_b32_e32 v30, 16, v237
	v_and_b32_e32 v31, 0xffff0000, v237
	v_cvt_pk_bf16_f32 v26, v26, v27
	v_cvt_pk_bf16_f32 v27, v32, v33
	v_lshlrev_b32_e32 v32, 16, v238
	v_and_b32_e32 v33, 0xffff0000, v238
	v_pk_add_f32 v[22:23], v[22:23], v[30:31]
	v_pk_add_f32 v[20:21], v[20:21], v[28:29]
	v_lshlrev_b32_e32 v34, 16, v239
	v_and_b32_e32 v35, 0xffff0000, v239
	v_pk_add_f32 v[30:31], v[16:17], v[32:33]
	v_mul_f32_e32 v16, v21, v21
	v_mul_f32_e32 v17, v23, v23
	v_pk_add_f32 v[28:29], v[18:19], v[34:35]
	v_fmac_f32_e32 v16, v20, v20
	v_fmac_f32_e32 v17, v22, v22
	v_add_f32_e32 v16, v16, v17
	v_mul_f32_e32 v17, v31, v31
	v_mul_f32_e32 v18, v29, v29
	v_fmac_f32_e32 v17, v30, v30
	v_fmac_f32_e32 v18, v28, v28
	v_add_f32_e32 v17, v17, v18
	v_add_f32_e32 v16, v16, v17
	v_add_f32_e32 v19, v36, v16
	ds_bpermute_b32 v34, v196, v19
	v_lshl_add_u64 v[16:17], s[16:17], 0, v[94:95]
	v_lshl_add_u64 v[32:33], v[168:169], 1, v[16:17]
	global_store_dwordx4 v[32:33], v[24:27], off
	v_cvt_pk_bf16_f32 v18, v20, v21
	s_waitcnt lgkmcnt(0)
	v_add_f32_e32 v16, v19, v34
	ds_bpermute_b32 v17, v197, v16
	v_cvt_pk_bf16_f32 v19, v22, v23
	v_cvt_pk_bf16_f32 v20, v30, v31
	v_cvt_pk_bf16_f32 v21, v28, v29
	global_store_dwordx4 v[32:33], v[18:21], off offset:256
	s_and_saveexec_b64 s[34:35], s[4:5]
	s_cbranch_execz .LBB0_1141
	v_lshlrev_b64 v[18:19], 6, v[92:93]
	v_lshl_add_u64 v[18:19], s[22:23], 0, v[18:19]
	v_lshl_add_u64 v[18:19], s[30:31], 2, v[18:19]
	s_lshl_b32 s10, s45, 2
	v_lshl_add_u64 v[18:19], v[18:19], 0, s[10:11]
	s_waitcnt lgkmcnt(0)
	v_add_f32_e32 v16, v16, v17
	global_store_dword v[18:19], v16, off
.LBB0_1141:
	s_or_b64 exec, exec, s[34:35]
	s_waitcnt vmcnt(15)
	v_lshlrev_b32_e32 v16, 16, v240
	s_waitcnt lgkmcnt(0)
	v_and_b32_e32 v17, 0xffff0000, v240
	v_lshlrev_b32_e32 v18, 16, v241
	v_and_b32_e32 v19, 0xffff0000, v241
	v_lshlrev_b32_e32 v20, 16, v242
	v_and_b32_e32 v21, 0xffff0000, v242
	v_lshlrev_b32_e32 v22, 16, v243
	v_and_b32_e32 v23, 0xffff0000, v243
	v_pk_add_f32 v[14:15], v[14:15], v[18:19]
	v_pk_add_f32 v[12:13], v[12:13], v[16:17]
	v_pk_add_f32 v[16:17], v[10:11], v[22:23]
	v_pk_add_f32 v[10:11], v[8:9], v[20:21]
	v_mul_f32_e32 v8, v13, v13
	v_mul_f32_e32 v9, v15, v15
	v_fmac_f32_e32 v8, v12, v12
	v_fmac_f32_e32 v9, v14, v14
	v_add_f32_e32 v8, v8, v9
	v_mul_f32_e32 v9, v11, v11
	v_mul_f32_e32 v18, v17, v17
	v_fmac_f32_e32 v9, v10, v10
	v_fmac_f32_e32 v18, v16, v16
	v_add_f32_e32 v9, v9, v18
	v_add_f32_e32 v20, v8, v9
	v_cvt_pk_bf16_f32 v8, v12, v13
	v_cvt_pk_bf16_f32 v9, v14, v15
	s_waitcnt vmcnt(14)
	v_lshlrev_b32_e32 v12, 16, v244
	v_and_b32_e32 v13, 0xffff0000, v244
	v_lshlrev_b32_e32 v14, 16, v245
	v_and_b32_e32 v15, 0xffff0000, v245
	v_cvt_pk_bf16_f32 v10, v10, v11
	v_cvt_pk_bf16_f32 v11, v16, v17
	v_lshlrev_b32_e32 v16, 16, v246
	v_and_b32_e32 v17, 0xffff0000, v246
	v_pk_add_f32 v[6:7], v[6:7], v[14:15]
	v_pk_add_f32 v[4:5], v[4:5], v[12:13]
	v_lshlrev_b32_e32 v18, 16, v247
	v_and_b32_e32 v19, 0xffff0000, v247
	v_pk_add_f32 v[14:15], v[0:1], v[16:17]
	v_mul_f32_e32 v0, v5, v5
	v_mul_f32_e32 v1, v7, v7
	v_pk_add_f32 v[12:13], v[2:3], v[18:19]
	v_fmac_f32_e32 v0, v4, v4
	v_fmac_f32_e32 v1, v6, v6
	v_add_f32_e32 v0, v0, v1
	v_mul_f32_e32 v1, v15, v15
	v_mul_f32_e32 v2, v13, v13
	v_fmac_f32_e32 v1, v14, v14
	v_fmac_f32_e32 v2, v12, v12
	v_add_f32_e32 v1, v1, v2
	v_add_f32_e32 v0, v0, v1
	v_add_f32_e32 v3, v20, v0
	ds_bpermute_b32 v18, v196, v3
	v_lshl_add_u64 v[0:1], s[16:17], 0, v[90:91]
	v_lshl_add_u64 v[16:17], v[168:169], 1, v[0:1]
	global_store_dwordx4 v[16:17], v[8:11], off
	v_cvt_pk_bf16_f32 v2, v4, v5
	s_waitcnt lgkmcnt(0)
	v_add_f32_e32 v0, v3, v18
	ds_bpermute_b32 v1, v197, v0
	v_cvt_pk_bf16_f32 v3, v6, v7
	v_cvt_pk_bf16_f32 v4, v14, v15
	v_cvt_pk_bf16_f32 v5, v12, v13
	global_store_dwordx4 v[16:17], v[2:5], off offset:256
	s_and_saveexec_b64 s[34:35], s[4:5]
	s_cbranch_execz .LBB0_1143
	v_lshlrev_b64 v[2:3], 6, v[88:89]
	v_lshl_add_u64 v[2:3], s[22:23], 0, v[2:3]
	v_lshl_add_u64 v[2:3], s[30:31], 2, v[2:3]
	s_lshl_b32 s10, s45, 2
	v_lshl_add_u64 v[2:3], v[2:3], 0, s[10:11]
	s_waitcnt lgkmcnt(0)
	v_add_f32_e32 v0, v0, v1
	global_store_dword v[2:3], v0, off
